# phase C triangular solve: v_pk_mul_f32 + two v_add_f32 fused into two v_fma_f32 (f32, single rounding) at 126 sites
# speedup vs baseline: 1.0052x; 1.0052x over previous
.LBB0_403:
	s_or_b64 exec, exec, s[0:1]
	v_xor_b32_e32 v0, 32, v49
	v_cmp_lt_i32_e64 s[0:1], v0, v50
	v_mov_b32_e32 v35, v18
	v_mov_b32_e32 v33, v16
	v_cndmask_b32_e64 v0, v49, v0, s[0:1]
	v_lshlrev_b32_e32 v237, 2, v0
	v_mul_u32_u24_e32 v0, 0x120, v185
	v_lshlrev_b32_e32 v236, 1, v0
	v_add_u32_e32 v0, 0xa000, v236
	ds_bpermute_b32 v4, v237, v72
	ds_read2_b64 v[0:3], v0 offset0:192 offset1:210
	ds_read_u16 v18, v236 offset:51856
	ds_read_b96 v[100:102], v236 offset:42784
	v_cmp_gt_u32_e64 s[0:1], 32, v48
	ds_read_b128 v[52:55], v236 offset:43648
	v_mov_b32_e32 v37, v20
	s_waitcnt lgkmcnt(4)
	v_cndmask_b32_e64 v16, v4, v72, s[0:1]
	s_waitcnt lgkmcnt(3)
	v_lshlrev_b32_e32 v4, 16, v0
	v_fma_f32 v48, v16, v4, v72
	v_lshlrev_b32_e32 v4, 16, v2
	s_waitcnt lgkmcnt(2)
	v_lshlrev_b32_e32 v58, 16, v18
	ds_read_u16 v18, v236 offset:52144
	v_fma_f32 v49, v16, v4, v6
	ds_bpermute_b32 v42, v237, v49
	ds_read_b64 v[4:5], v236 offset:42928
	s_waitcnt lgkmcnt(4)
	v_lshlrev_b32_e32 v6, 16, v100
	v_fma_f32 v50, v16, v6, v80
	s_waitcnt lgkmcnt(2)
	v_lshlrev_b32_e32 v80, 16, v18
	v_add_u32_e32 v18, 0xa800, v236
	ds_read2_b64 v[108:111], v18 offset0:82 offset1:98
	ds_read_u16 v20, v236 offset:53008
	ds_read_b128 v[112:115], v236 offset:43936
	s_waitcnt lgkmcnt(4)
	v_cndmask_b32_e64 v42, v42, v49, s[0:1]
	v_and_b32_e32 v0, 0xffff0000, v0
	v_fmac_f32_e32 v48, v42, v0
	v_and_b32_e32 v0, 0xffff0000, v2
	s_waitcnt lgkmcnt(3)
	v_lshlrev_b32_e32 v6, 16, v4
	v_fmac_f32_e32 v49, v42, v0
	v_and_b32_e32 v0, 0xffff0000, v100
	v_fma_f32 v6, v16, v6, v44
	v_lshlrev_b32_e32 v18, 16, v52
	v_fmac_f32_e32 v50, v42, v0
	v_and_b32_e32 v0, 0xffff0000, v4
	v_fma_f32 v44, v16, v18, v46
	s_waitcnt lgkmcnt(2)
	v_lshlrev_b32_e32 v18, 16, v110
	v_fmac_f32_e32 v6, v42, v0
	v_and_b32_e32 v0, 0xffff0000, v52
	v_fma_f32 v59, v16, v18, v62
	s_waitcnt lgkmcnt(1)
	v_lshlrev_b32_e32 v46, 16, v20
	s_waitcnt lgkmcnt(0)
	v_lshlrev_b32_e32 v18, 16, v112
	ds_read_b128 v[128:131], v236 offset:53152
	ds_read_b32 v20, v236 offset:44080
	v_fmac_f32_e32 v44, v42, v0
	v_and_b32_e32 v0, 0xffff0000, v110
	v_fma_f32 v51, v16, v18, v64
	v_fmac_f32_e32 v59, v42, v0
	v_and_b32_e32 v0, 0xffff0000, v112
	v_fmac_f32_e32 v51, v42, v0
	ds_bpermute_b32 v0, v237, v50
	s_waitcnt lgkmcnt(1)
	v_lshlrev_b32_e32 v43, 16, v20
	v_fma_f32 v62, v16, v43, v68
	v_and_b32_e32 v2, 0xffff0000, v20
	ds_read_b32 v18, v236 offset:53296
	ds_read_u16 v4, v236 offset:44084
	ds_read_b128 v[116:119], v236 offset:43802
	v_fmac_f32_e32 v62, v42, v2
	s_waitcnt lgkmcnt(3)
	v_cndmask_b32_e64 v0, v0, v50, s[0:1]
	v_lshlrev_b32_e32 v2, 16, v1
	v_fmac_f32_e32 v48, v0, v2
	v_lshlrev_b32_e32 v2, 16, v3
	v_fmac_f32_e32 v49, v0, v2
	v_lshlrev_b32_e32 v2, 16, v101
	v_fmac_f32_e32 v50, v0, v2
	v_lshlrev_b32_e32 v2, 16, v5
	v_fmac_f32_e32 v6, v0, v2
	v_lshlrev_b32_e32 v2, 16, v53
	v_fmac_f32_e32 v44, v0, v2
	v_lshlrev_b32_e32 v2, 16, v111
	v_lshlrev_b32_e32 v20, 16, v113
	s_waitcnt lgkmcnt(1)
	v_lshlrev_b32_e32 v4, 16, v4
	v_fmac_f32_e32 v59, v0, v2
	ds_read_u16 v2, v236 offset:53300
	v_fmac_f32_e32 v51, v0, v20
	v_fmac_f32_e32 v62, v0, v4
	ds_bpermute_b32 v0, v237, v6
	ds_read_u16 v4, v236 offset:42648
	ds_read_b128 v[136:139], v236 offset:53010
	v_mov_b32_e32 v34, v86
	v_mov_b32_e32 v38, v90
	s_waitcnt lgkmcnt(3)
	v_lshlrev_b32_e32 v20, 16, v2
	v_and_b32_e32 v1, 0xffff0000, v1
	v_and_b32_e32 v2, 0xffff0000, v3
	v_and_b32_e32 v3, 0xffff0000, v101
	ds_read_u16 v86, v236 offset:42936
	ds_read_u16 v90, v236 offset:43800
	s_waitcnt lgkmcnt(3)
	v_lshlrev_b32_e32 v72, 16, v4
	v_cndmask_b32_e64 v4, v0, v6, s[0:1]
	v_fmac_f32_e32 v48, v4, v1
	v_fmac_f32_e32 v49, v4, v2
	v_fmac_f32_e32 v50, v4, v3
	ds_read_b128 v[0:3], v236 offset:44086
	v_and_b32_e32 v42, 0xffff0000, v53
	v_and_b32_e32 v43, 0xffff0000, v111
	v_and_b32_e32 v52, 0xffff0000, v113
	v_fmac_f32_e32 v44, v4, v42
	v_fmac_f32_e32 v59, v4, v43
	ds_read_b128 v[110:113], v236 offset:53302
	s_waitcnt lgkmcnt(1)
	v_and_b32_e32 v43, 0xffff0000, v0
	v_lshlrev_b32_e32 v42, 16, v0
	ds_read_b32 v0, v236 offset:42938
	v_and_b32_e32 v5, 0xffff0000, v5
	v_fmac_f32_e32 v6, v4, v5
	ds_bpermute_b32 v5, v237, v48
	v_fmac_f32_e32 v51, v4, v52
	v_and_b32_e32 v53, 0xffff0000, v1
	v_lshlrev_b32_e32 v52, 16, v1
	v_and_b32_e32 v57, 0xffff0000, v2
	v_lshlrev_b32_e32 v56, 16, v2
	v_and_b32_e32 v61, 0xffff0000, v3
	v_lshlrev_b32_e32 v60, 16, v3
	s_waitcnt lgkmcnt(1)
	v_and_b32_e32 v127, 0xffff0000, v0
	v_lshlrev_b32_e32 v126, 16, v0
	ds_read_b128 v[0:3], v236 offset:52864
	s_waitcnt lgkmcnt(1)
	v_cndmask_b32_e64 v5, v48, v5, s[0:1]
	v_fmac_f32_e32 v49, v5, v72
	v_mov_b32_e32 v32, v84
	v_mov_b32_e32 v40, v92
	v_lshlrev_b32_e32 v84, 16, v102
	v_and_b32_e32 v92, 0xffff0000, v102
	v_and_b32_e32 v103, 0xffff0000, v112
	v_lshlrev_b32_e32 v102, 16, v112
	v_and_b32_e32 v101, 0xffff0000, v113
	v_lshlrev_b32_e32 v100, 16, v113
	v_and_b32_e32 v113, 0xffff0000, v119
	v_lshlrev_b32_e32 v112, 16, v119
	v_and_b32_e32 v121, 0xffff0000, v118
	v_lshlrev_b32_e32 v120, 16, v118
	s_waitcnt lgkmcnt(0)
	v_and_b32_e32 v119, 0xffff0000, v0
	v_lshlrev_b32_e32 v118, 16, v0
	ds_bpermute_b32 v0, v237, v49
	v_fmac_f32_e32 v50, v5, v84
	v_pk_mul_f32 v[42:43], v[4:5], v[42:43]
	v_mov_b32_e32 v36, v88
	v_lshlrev_b32_e32 v88, 16, v54
	s_waitcnt lgkmcnt(0)
	v_cndmask_b32_e64 v133, v49, v0, s[0:1]
	v_fmac_f32_e32 v50, v133, v92
	v_add_f32_e32 v0, v62, v42
	ds_bpermute_b32 v42, v237, v50
	v_and_b32_e32 v107, 0xffff0000, v110
	v_lshlrev_b32_e32 v106, 16, v110
	v_and_b32_e32 v105, 0xffff0000, v111
	v_lshlrev_b32_e32 v104, 16, v111
	v_and_b32_e32 v111, 0xffff0000, v114
	v_lshlrev_b32_e32 v110, 16, v114
	v_lshlrev_b32_e32 v86, 16, v86
	v_lshlrev_b32_e32 v90, 16, v90
	v_mov_b32_e32 v132, v5
	v_fmac_f32_e32 v6, v5, v86
	v_fmac_f32_e32 v44, v5, v88
	v_fmac_f32_e32 v59, v5, v90
	v_add_f32_e32 v0, v0, v43
	s_waitcnt lgkmcnt(0)
	v_cndmask_b32_e64 v43, v50, v42, s[0:1]
	v_mov_b32_e32 v42, v133
	v_fma_f32 v4, v132, v110, v51
	v_fma_f32 v62, v133, v111, v4
	v_lshlrev_b32_e32 v64, 16, v128
	v_fma_f32 v4, v42, v126, v6
	v_fma_f32 v51, v43, v127, v4
	ds_bpermute_b32 v6, v237, v51
	v_and_b32_e32 v16, 0xffff0000, v128
	v_and_b32_e32 v128, 0xffff0000, v54
	v_and_b32_e32 v125, 0xffff0000, v55
	v_lshlrev_b32_e32 v124, 16, v55
	v_and_b32_e32 v55, 0xffff0000, v116
	v_lshlrev_b32_e32 v54, 16, v116
	v_fmac_f32_e32 v44, v133, v128
	v_fma_f32 v4, v42, v54, v59
	v_fma_f32 v59, v43, v55, v4
	v_pk_mul_f32 v[4:5], v[42:43], v[52:53]
	v_mov_b32_e32 v42, v43
	s_waitcnt lgkmcnt(0)
	v_cndmask_b32_e64 v43, v51, v6, s[0:1]
	v_add_f32_e32 v0, v0, v4
	v_fma_f32 v4, v42, v124, v44
	v_fma_f32 v44, v43, v125, v4
	ds_bpermute_b32 v72, v237, v44
	ds_read_b64 v[132:133], v236 offset:44102
	v_add_f32_e32 v0, v0, v5
	ds_read_b96 v[4:6], v236 offset:43952
	v_and_b32_e32 v123, 0xffff0000, v117
	v_lshlrev_b32_e32 v122, 16, v117
	v_and_b32_e32 v117, 0xffff0000, v115
	v_lshlrev_b32_e32 v116, 16, v115
	v_pk_mul_f32 v[52:53], v[42:43], v[116:117]
	s_waitcnt lgkmcnt(2)
	v_cndmask_b32_e64 v117, v72, v44, s[0:1]
	v_mov_b32_e32 v116, v43
	s_waitcnt lgkmcnt(0)
	v_and_b32_e32 v43, 0xffff0000, v5
	v_lshlrev_b32_e32 v42, 16, v5
	v_fma_f32 v5, v116, v122, v59
	v_fma_f32 v59, v117, v123, v5
	ds_bpermute_b32 v72, v237, v59
	v_add_f32_e32 v5, v62, v52
	v_add_f32_e32 v62, v5, v53
	v_and_b32_e32 v5, 0xffff0000, v4
	v_lshlrev_b32_e32 v4, 16, v4
	s_waitcnt lgkmcnt(0)
	v_cndmask_b32_e64 v53, v72, v59, s[0:1]
	v_mov_b32_e32 v52, v117
	v_and_b32_e32 v55, 0xffff0000, v109
	v_fma_f32 v4, v52, v4, v62
	v_fma_f32 v62, v53, v5, v4
	ds_bpermute_b32 v72, v237, v62
	v_pk_mul_f32 v[4:5], v[116:117], v[56:57]
	v_and_b32_e32 v57, 0xffff0000, v108
	v_add_f32_e32 v0, v0, v4
	v_add_f32_e32 v0, v0, v5
	s_waitcnt lgkmcnt(0)
	v_cndmask_b32_e64 v5, v72, v62, s[0:1]
	v_mov_b32_e32 v4, v53
	v_lshlrev_b32_e32 v56, 16, v108
	v_fma_f32 v0, v4, v60, v0
	v_fma_f32 v0, v5, v61, v0
	ds_bpermute_b32 v60, v237, v0
	v_pk_mul_f32 v[52:53], v[52:53], v[56:57]
	v_lshlrev_b32_e32 v54, 16, v109
	v_add_f32_e32 v44, v44, v52
	v_mov_b32_e32 v56, v5
	s_waitcnt lgkmcnt(0)
	v_cndmask_b32_e64 v57, v60, v0, s[0:1]
	v_add_f32_e32 v44, v44, v53
	v_fma_f32 v44, v56, v54, v44
	v_fma_f32 v52, v57, v55, v44
	ds_bpermute_b32 v44, v237, v52
	v_fma_f32 v4, v4, v120, v59
	v_fma_f32 v53, v5, v121, v4
	v_pk_mul_f32 v[4:5], v[56:57], v[42:43]
	v_mov_b32_e32 v42, v57
	s_waitcnt lgkmcnt(0)
	v_cndmask_b32_e64 v43, v52, v44, s[0:1]
	v_add_f32_e32 v4, v62, v4
	v_fma_f32 v44, v42, v112, v53
	v_fma_f32 v53, v43, v113, v44
	ds_bpermute_b32 v44, v237, v53
	v_add_f32_e32 v56, v4, v5
	v_and_b32_e32 v5, 0xffff0000, v6
	v_lshlrev_b32_e32 v4, 16, v6
	v_mov_b32_e32 v54, v43
	s_waitcnt lgkmcnt(0)
	v_cndmask_b32_e64 v55, v53, v44, s[0:1]
	v_and_b32_e32 v127, 0xffff0000, v132
	v_fma_f32 v4, v54, v4, v56
	v_fma_f32 v54, v55, v5, v4
	ds_bpermute_b32 v6, v237, v54
	v_lshlrev_b32_e32 v126, 16, v132
	v_pk_mul_f32 v[4:5], v[42:43], v[126:127]
	v_and_b32_e32 v43, 0xffff0000, v133
	v_add_f32_e32 v0, v0, v4
	v_add_f32_e32 v0, v0, v5
	s_waitcnt lgkmcnt(0)
	v_cndmask_b32_e64 v5, v54, v6, s[0:1]
	v_lshlrev_b32_e32 v42, 16, v133
	v_mov_b32_e32 v4, v55
	v_mov_b32_e32 v39, v22
	ds_bpermute_b32 v22, v237, v73
	ds_read_b64 v[108:109], v236 offset:53318
	ds_read_b64 v[56:57], v236 offset:53026
	v_fma_f32 v0, v4, v42, v0
	v_fma_f32 v55, v5, v43, v0
	ds_read_b96 v[4:6], v236 offset:52146
	ds_read_b96 v[42:44], v236 offset:52000
	s_waitcnt lgkmcnt(4)
	v_cndmask_b32_e64 v146, v22, v73, s[0:1]
	v_fmac_f32_e32 v7, v146, v58
	v_and_b32_e32 v111, 0xffff0000, v129
	v_lshlrev_b32_e32 v110, 16, v129
	s_waitcnt lgkmcnt(1)
	v_and_b32_e32 v129, 0xffff0000, v6
	v_lshlrev_b32_e32 v128, 16, v6
	ds_bpermute_b32 v6, v237, v7
	v_and_b32_e32 v113, 0xffff0000, v57
	v_lshlrev_b32_e32 v112, 16, v57
	v_and_b32_e32 v117, 0xffff0000, v56
	v_lshlrev_b32_e32 v116, 16, v56
	ds_read_b64 v[56:57], v236 offset:51858
	ds_read_b64 v[60:61], v236 offset:51712
	v_and_b32_e32 v123, 0xffff0000, v139
	v_lshlrev_b32_e32 v122, 16, v139
	v_and_b32_e32 v127, 0xffff0000, v138
	v_lshlrev_b32_e32 v126, 16, v138
	v_and_b32_e32 v139, 0xffff0000, v5
	v_lshlrev_b32_e32 v138, 16, v5
	v_and_b32_e32 v145, 0xffff0000, v4
	v_lshlrev_b32_e32 v144, 16, v4
	s_waitcnt lgkmcnt(3)
	v_and_b32_e32 v5, 0xffff0000, v42
	v_lshlrev_b32_e32 v4, 16, v42
	s_waitcnt lgkmcnt(2)
	v_cndmask_b32_e64 v147, v6, v7, s[0:1]
	v_and_b32_e32 v115, 0xffff0000, v136
	v_lshlrev_b32_e32 v114, 16, v136
	v_and_b32_e32 v125, 0xffff0000, v3
	v_lshlrev_b32_e32 v124, 16, v3
	v_and_b32_e32 v133, 0xffff0000, v2
	v_lshlrev_b32_e32 v132, 16, v2
	v_and_b32_e32 v3, 0xffff0000, v137
	v_lshlrev_b32_e32 v2, 16, v137
	s_waitcnt lgkmcnt(1)
	v_and_b32_e32 v137, 0xffff0000, v57
	v_lshlrev_b32_e32 v136, 16, v57
	v_mov_b32_e32 v57, v8
	v_fma_f32 v8, v146, v4, v81
	v_fma_f32 v8, v147, v5, v8
	s_waitcnt lgkmcnt(0)
	v_and_b32_e32 v151, 0xffff0000, v60
	v_lshlrev_b32_e32 v150, 16, v60
	v_mov_b32_e32 v59, v10
	ds_bpermute_b32 v10, v237, v8
	v_mov_b32_e32 v62, v82
	v_fma_f32 v6, v146, v150, v73
	ds_read_b64 v[72:73], v236 offset:52880
	v_fmac_f32_e32 v45, v146, v80
	ds_read_b96 v[80:82], v236 offset:53168
	v_and_b32_e32 v149, 0xffff0000, v56
	v_lshlrev_b32_e32 v148, 16, v56
	v_fma_f32 v22, v147, v151, v6
	s_waitcnt lgkmcnt(2)
	v_cndmask_b32_e64 v151, v10, v8, s[0:1]
	v_mov_b32_e32 v150, v147
	v_and_b32_e32 v141, 0xffff0000, v1
	v_lshlrev_b32_e32 v140, 16, v1
	v_and_b32_e32 v1, 0xffff0000, v61
	v_lshlrev_b32_e32 v0, 16, v61
	v_mov_b32_e32 v61, v12
	v_fmac_f32_e32 v63, v146, v46
	v_fma_f32 v12, v146, v118, v47
	s_waitcnt lgkmcnt(0)
	v_and_b32_e32 v47, 0xffff0000, v81
	v_lshlrev_b32_e32 v46, 16, v81
	v_fma_f32 v10, v150, v148, v7
	v_and_b32_e32 v7, 0xffff0000, v80
	v_lshlrev_b32_e32 v6, 16, v80
	v_and_b32_e32 v135, 0xffff0000, v44
	v_lshlrev_b32_e32 v134, 16, v44
	v_fma_f32 v44, v150, v144, v45
	v_mov_b32_e32 v56, v66
	v_fma_f32 v66, v151, v145, v44
	v_fmac_f32_e32 v65, v146, v64
	ds_bpermute_b32 v64, v237, v66
	v_mov_b32_e32 v80, v151
	v_lshlrev_b32_e32 v68, 16, v18
	v_fmac_f32_e32 v65, v147, v16
	s_waitcnt lgkmcnt(0)
	v_cndmask_b32_e64 v81, v64, v66, s[0:1]
	v_fma_f32 v16, v150, v114, v63
	v_fma_f32 v0, v80, v0, v22
	v_fma_f32 v0, v81, v1, v0
	ds_bpermute_b32 v1, v237, v0
	v_and_b32_e32 v18, 0xffff0000, v18
	v_fmac_f32_e32 v69, v146, v68
	v_fma_f32 v16, v151, v115, v16
	v_pk_mul_f32 v[44:45], v[80:81], v[110:111]
	v_and_b32_e32 v143, 0xffff0000, v43
	v_lshlrev_b32_e32 v142, 16, v43
	v_fmac_f32_e32 v69, v147, v18
	v_add_f32_e32 v18, v65, v44
	s_waitcnt lgkmcnt(0)
	v_cndmask_b32_e64 v65, v0, v1, s[0:1]
	v_mov_b32_e32 v64, v81
	v_fma_f32 v12, v147, v119, v12
	v_fma_f32 v10, v151, v149, v10
	v_pk_mul_f32 v[114:115], v[80:81], v[142:143]
	v_pk_mul_f32 v[118:119], v[80:81], v[140:141]
	v_fmac_f32_e32 v69, v151, v20
	v_fma_f32 v1, v64, v136, v10
	v_fma_f32 v1, v65, v137, v1
	ds_bpermute_b32 v20, v237, v1
	v_add_f32_e32 v18, v18, v45
	v_pk_mul_f32 v[44:45], v[64:65], v[106:107]
	v_add_f32_e32 v8, v8, v114
	v_add_f32_e32 v22, v69, v44
	s_waitcnt lgkmcnt(0)
	v_cndmask_b32_e64 v69, v1, v20, s[0:1]
	v_mov_b32_e32 v68, v65
	v_add_f32_e32 v8, v8, v115
	v_pk_mul_f32 v[110:111], v[64:65], v[138:139]
	v_pk_mul_f32 v[2:3], v[64:65], v[2:3]
	v_add_f32_e32 v16, v16, v2
	v_fma_f32 v2, v68, v134, v8
	v_add_f32_e32 v10, v66, v110
	v_fma_f32 v2, v69, v135, v2
	v_add_f32_e32 v8, v10, v111
	ds_bpermute_b32 v10, v237, v2
	v_and_b32_e32 v121, 0xffff0000, v131
	v_lshlrev_b32_e32 v120, 16, v131
	v_and_b32_e32 v131, 0xffff0000, v130
	v_lshlrev_b32_e32 v130, 16, v130
	s_waitcnt lgkmcnt(0)
	v_cndmask_b32_e64 v107, v2, v10, s[0:1]
	v_mov_b32_e32 v106, v69
	v_pk_mul_f32 v[64:65], v[68:69], v[132:133]
	v_pk_mul_f32 v[80:81], v[68:69], v[130:131]
	v_add_f32_e32 v16, v16, v3
	v_fma_f32 v3, v106, v128, v8
	v_fma_f32 v3, v107, v129, v3
	ds_bpermute_b32 v8, v237, v3
	v_add_f32_e32 v12, v12, v118
	v_add_f32_e32 v12, v12, v119
	v_add_f32_e32 v12, v12, v64
	v_add_f32_e32 v12, v12, v65
	s_waitcnt lgkmcnt(0)
	v_cndmask_b32_e64 v65, v3, v8, s[0:1]
	v_mov_b32_e32 v64, v107
	v_add_f32_e32 v10, v18, v80
	v_fma_f32 v8, v64, v124, v12
	v_fma_f32 v8, v65, v125, v8
	ds_bpermute_b32 v12, v237, v8
	v_add_f32_e32 v18, v22, v45
	v_add_f32_e32 v10, v10, v81
	v_fma_f32 v16, v106, v126, v16
	v_fma_f32 v16, v107, v127, v16
	s_waitcnt lgkmcnt(0)
	v_cndmask_b32_e64 v45, v12, v8, s[0:1]
	v_mov_b32_e32 v44, v65
	v_fma_f32 v12, v44, v122, v16
	v_fma_f32 v12, v45, v123, v12
	ds_bpermute_b32 v16, v237, v12
	v_fma_f32 v10, v64, v120, v10
	v_fma_f32 v10, v65, v121, v10
	v_mov_b32_e32 v64, v45
	s_waitcnt lgkmcnt(0)
	v_cndmask_b32_e64 v65, v16, v12, s[0:1]
	v_fma_f32 v18, v106, v104, v18
	v_fma_f32 v6, v64, v6, v10
	v_fma_f32 v10, v65, v7, v6
	ds_bpermute_b32 v16, v237, v10
	v_fma_f32 v18, v107, v105, v18
	v_and_b32_e32 v5, 0xffff0000, v73
	v_fma_f32 v6, v44, v102, v18
	v_fma_f32 v18, v45, v103, v6
	s_waitcnt lgkmcnt(0)
	v_cndmask_b32_e64 v7, v16, v10, s[0:1]
	v_mov_b32_e32 v6, v65
	v_lshlrev_b32_e32 v4, 16, v73
	v_fma_f32 v16, v6, v100, v18
	v_fma_f32 v16, v7, v101, v16
	ds_bpermute_b32 v18, v237, v16
	v_and_b32_e32 v73, 0xffff0000, v72
	v_lshlrev_b32_e32 v72, 16, v72
	v_and_b32_e32 v43, 0xffff0000, v108
	v_fma_f32 v8, v64, v72, v8
	v_fma_f32 v8, v65, v73, v8
	s_waitcnt lgkmcnt(0)
	v_cndmask_b32_e64 v45, v18, v16, s[0:1]
	v_mov_b32_e32 v44, v7
	v_fma_f32 v4, v44, v4, v8
	v_fma_f32 v4, v45, v5, v4
	ds_bpermute_b32 v5, v237, v4
	v_fma_f32 v6, v6, v116, v12
	v_fma_f32 v8, v7, v117, v6
	v_pk_mul_f32 v[6:7], v[44:45], v[46:47]
	v_mov_b32_e32 v46, v45
	s_waitcnt lgkmcnt(0)
	v_cndmask_b32_e64 v47, v4, v5, s[0:1]
	v_add_f32_e32 v6, v10, v6
	v_fma_f32 v5, v46, v112, v8
	v_fma_f32 v5, v47, v113, v5
	ds_bpermute_b32 v8, v237, v5
	v_add_f32_e32 v10, v6, v7
	v_and_b32_e32 v7, 0xffff0000, v82
	v_lshlrev_b32_e32 v6, 16, v82
	v_mov_b32_e32 v44, v47
	s_waitcnt lgkmcnt(0)
	v_cndmask_b32_e64 v45, v5, v8, s[0:1]
	v_lshlrev_b32_e32 v42, 16, v108
	v_fma_f32 v6, v44, v6, v10
	v_fma_f32 v6, v45, v7, v6
	ds_bpermute_b32 v7, v237, v6
	v_mul_u32_u24_e32 v10, 0x48, v154
	v_fma_f32 v8, v46, v42, v16
	v_fma_f32 v8, v47, v43, v8
	s_waitcnt lgkmcnt(0)
	v_cndmask_b32_e64 v43, v6, v7, s[0:1]
	v_and_b32_e32 v47, 0xffff0000, v109
	v_lshlrev_b32_e32 v46, 16, v109
	v_mov_b32_e32 v42, v45
	v_or_b32_e32 v10, v10, v41
	v_lshlrev_b32_e32 v16, 1, v10
	v_fma_f32 v7, v42, v46, v8
	v_add_u32_e32 v10, 0xa000, v16
	v_fma_f32 v7, v43, v47, v7
	ds_read2_b64 v[42:45], v10 offset0:192 offset1:194
	v_mov_b32_e32 v63, v14
	v_add_u32_e32 v14, 0xc800, v16
	v_cmp_gt_u32_e64 s[4:5], 16, v154
	v_mov_b32_e32 v8, v67
	ds_read2_b64 v[64:67], v14 offset0:64 offset1:66
	s_waitcnt lgkmcnt(1)
	v_cndmask_b32_e64 v45, v45, 0, s[4:5]
	v_cndmask_b32_e64 v44, v44, 0, s[4:5]
	v_cndmask_b32_e64 v43, v43, 0, s[4:5]
	v_cndmask_b32_e64 v42, v42, 0, s[4:5]
	v_mov_b32_e32 v58, v70
	v_mov_b32_e32 v60, v74
	v_cvt_pk_bf16_f32 v102, v48, v49
	v_cvt_pk_bf16_f32 v103, v50, v51
	v_cvt_pk_bf16_f32 v104, v52, v53
	v_cvt_pk_bf16_f32 v105, v54, v55
	v_add_u32_e32 v100, 0xb800, v16
	v_mov_b32_e32 v10, v71
	v_mfma_f32_32x32x16_bf16 v[48:63], v[42:45], v[102:105], v[48:63]
	s_waitcnt lgkmcnt(0)
	v_cndmask_b32_e64 v45, v67, 0, s[4:5]
	v_cndmask_b32_e64 v44, v66, 0, s[4:5]
	v_cndmask_b32_e64 v43, v65, 0, s[4:5]
	v_cndmask_b32_e64 v42, v64, 0, s[4:5]
	ds_read2_b64 v[64:67], v100 offset1:2
	v_mov_b32_e32 v12, v75
	v_mov_b32_e32 v14, v83
	v_cvt_pk_bf16_f32 v68, v0, v1
	v_cvt_pk_bf16_f32 v69, v2, v3
	v_cvt_pk_bf16_f32 v70, v4, v5
	v_cvt_pk_bf16_f32 v71, v6, v7
	v_mov_b32_e32 v41, v24
	v_mov_b32_e32 v46, v98
	v_mfma_f32_32x32x16_bf16 v[0:15], v[42:45], v[68:71], v[0:15]
	v_mov_b32_e32 v42, v94
	v_mov_b32_e32 v43, v26
	v_mov_b32_e32 v44, v96
	v_mov_b32_e32 v45, v28
	v_mov_b32_e32 v47, v30
	v_add_u32_e32 v98, 0xd800, v16
	v_mov_b32_e32 v16, v85
	s_waitcnt lgkmcnt(0)
	v_mfma_f32_32x32x16_bf16 v[32:47], v[64:67], v[102:105], v[32:47]
	ds_read2_b64 v[64:67], v98 offset0:128 offset1:130
	v_mov_b32_e32 v18, v87
	v_mov_b32_e32 v20, v89
	v_mov_b32_e32 v22, v91
	v_mov_b32_e32 v24, v93
	v_mov_b32_e32 v26, v95
	v_mov_b32_e32 v28, v97
	v_mov_b32_e32 v30, v99
	ds_bpermute_b32 v99, v237, v56
	ds_bpermute_b32 v101, v237, v8
	s_waitcnt lgkmcnt(2)
	v_mfma_f32_32x32x16_bf16 v[16:31], v[64:67], v[68:71], v[16:31]
	ds_read_u16 v64, v236 offset:44976
	ds_read_u16 v65, v236 offset:54192
	ds_read_u16 v66, v236 offset:45264
	ds_read_u16 v67, v236 offset:54480
	ds_read_u16 v68, v236 offset:46128
	s_waitcnt lgkmcnt(4)
	v_lshlrev_b32_e32 v199, 16, v64
	s_waitcnt lgkmcnt(3)
	v_lshlrev_b32_e32 v200, 16, v65
	s_waitcnt lgkmcnt(2)
	v_lshlrev_b32_e32 v201, 16, v66
	s_waitcnt lgkmcnt(1)
	v_lshlrev_b32_e32 v202, 16, v67
	s_waitcnt lgkmcnt(0)
	v_lshlrev_b32_e32 v203, 16, v68
	ds_read_u16 v68, v236 offset:55344
	ds_read_b128 v[80:83], v236 offset:46272
	ds_read_b128 v[64:67], v236 offset:55488
	ds_read_b32 v69, v236 offset:46416
	ds_read_b32 v70, v236 offset:55632
	s_waitcnt lgkmcnt(4)
	v_lshlrev_b32_e32 v204, 16, v68
	v_cndmask_b32_e64 v198, v99, v56, s[0:1]
	s_waitcnt lgkmcnt(2)
	v_lshlrev_b32_e32 v206, 16, v64
	v_and_b32_e32 v240, 0xffff0000, v64
	ds_read_u16 v64, v236 offset:46420
	ds_read_u16 v68, v236 offset:55636
	ds_read_b128 v[94:97], v236 offset:45984
	ds_read_b128 v[106:109], v236 offset:46422
	ds_read_b128 v[72:75], v236 offset:55346
	s_waitcnt lgkmcnt(6)
	v_lshlrev_b32_e32 v207, 16, v69
	s_waitcnt lgkmcnt(5)
	v_lshlrev_b32_e32 v238, 16, v70
	v_and_b32_e32 v241, 0xffff0000, v69
	v_and_b32_e32 v242, 0xffff0000, v70
	s_waitcnt lgkmcnt(3)
	v_lshlrev_b32_e32 v244, 16, v68
	ds_read_b128 v[68:71], v236 offset:55200
	s_waitcnt lgkmcnt(2)
	v_and_b32_e32 v121, 0xffff0000, v106
	v_lshlrev_b32_e32 v120, 16, v106
	ds_read_b128 v[110:113], v236 offset:55638
	v_and_b32_e32 v123, 0xffff0000, v107
	v_lshlrev_b32_e32 v122, 16, v107
	ds_read_b64 v[106:107], v236 offset:46146
	v_and_b32_e32 v125, 0xffff0000, v108
	s_waitcnt lgkmcnt(1)
	v_and_b32_e32 v87, 0xffff0000, v110
	v_lshlrev_b32_e32 v86, 16, v110
	v_and_b32_e32 v85, 0xffff0000, v111
	v_lshlrev_b32_e32 v84, 16, v111
	v_lshlrev_b32_e32 v124, 16, v108
	ds_read_b64 v[110:111], v236 offset:46438
	s_waitcnt lgkmcnt(1)
	v_and_b32_e32 v129, 0xffff0000, v107
	v_lshlrev_b32_e32 v128, 16, v107
	v_and_b32_e32 v131, 0xffff0000, v106
	v_lshlrev_b32_e32 v130, 16, v106
	ds_read_b96 v[106:108], v236 offset:45266
	v_and_b32_e32 v93, 0xffff0000, v68
	v_lshlrev_b32_e32 v92, 16, v68
	v_fma_f32 v68, v198, v199, v57
	v_lshlrev_b32_e32 v205, 16, v80
	v_and_b32_e32 v239, 0xffff0000, v80
	ds_read_b128 v[102:105], v236 offset:46130
	v_lshlrev_b32_e32 v243, 16, v64
	v_and_b32_e32 v119, 0xffff0000, v81
	v_lshlrev_b32_e32 v118, 16, v81
	v_and_b32_e32 v89, 0xffff0000, v65
	v_lshlrev_b32_e32 v88, 16, v65
	v_and_b32_e32 v65, 0xffff0000, v112
	v_lshlrev_b32_e32 v64, 16, v112
	v_and_b32_e32 v127, 0xffff0000, v109
	v_lshlrev_b32_e32 v126, 16, v109
	v_and_b32_e32 v81, 0xffff0000, v113
	v_lshlrev_b32_e32 v80, 16, v113
	s_waitcnt lgkmcnt(2)
	v_and_b32_e32 v113, 0xffff0000, v110
	v_lshlrev_b32_e32 v112, 16, v110
	s_waitcnt lgkmcnt(1)
	v_and_b32_e32 v139, 0xffff0000, v108
	v_lshlrev_b32_e32 v138, 16, v108
	ds_read_b96 v[108:110], v236 offset:45120
	ds_bpermute_b32 v57, v237, v68
	v_and_b32_e32 v115, 0xffff0000, v94
	v_lshlrev_b32_e32 v114, 16, v94
	v_and_b32_e32 v91, 0xffff0000, v72
	s_waitcnt lgkmcnt(1)
	v_and_b32_e32 v153, 0xffff0000, v109
	v_lshlrev_b32_e32 v152, 16, v109
	v_and_b32_e32 v109, 0xffff0000, v108
	v_lshlrev_b32_e32 v108, 16, v108
	s_waitcnt lgkmcnt(0)
	v_cndmask_b32_e64 v199, v57, v68, s[0:1]
	v_fma_f32 v58, v198, v108, v58
	v_lshlrev_b32_e32 v90, 16, v72
	v_fma_f32 v72, v199, v109, v58
	v_fma_f32 v58, v198, v114, v60
	v_fma_f32 v99, v199, v115, v58
	ds_bpermute_b32 v58, v237, v72
	v_and_b32_e32 v137, 0xffff0000, v83
	v_lshlrev_b32_e32 v136, 16, v83
	v_and_b32_e32 v141, 0xffff0000, v82
	v_lshlrev_b32_e32 v140, 16, v82
	ds_read_b64 v[82:83], v236 offset:44978
	ds_read_b64 v[146:147], v236 offset:44832
	v_and_b32_e32 v143, 0xffff0000, v110
	v_lshlrev_b32_e32 v142, 16, v110
	v_and_b32_e32 v149, 0xffff0000, v107
	v_lshlrev_b32_e32 v148, 16, v107
	v_and_b32_e32 v107, 0xffff0000, v106
	v_lshlrev_b32_e32 v106, 16, v106
	v_fma_f32 v110, v198, v205, v62
	v_fma_f32 v205, v198, v207, v63
	v_mov_b32_e32 v62, v199
	s_waitcnt lgkmcnt(2)
	v_cndmask_b32_e64 v63, v58, v72, s[0:1]
	v_fma_f32 v60, v198, v201, v59
	v_and_b32_e32 v151, 0xffff0000, v95
	v_lshlrev_b32_e32 v150, 16, v95
	s_waitcnt lgkmcnt(0)
	v_and_b32_e32 v95, 0xffff0000, v147
	v_lshlrev_b32_e32 v94, 16, v147
	v_and_b32_e32 v147, 0xffff0000, v146
	v_lshlrev_b32_e32 v146, 16, v146
	v_fma_f32 v58, v62, v106, v60
	v_and_b32_e32 v117, 0xffff0000, v102
	v_lshlrev_b32_e32 v116, 16, v102
	v_and_b32_e32 v197, 0xffff0000, v82
	v_lshlrev_b32_e32 v196, 16, v82
	v_pk_mul_f32 v[146:147], v[198:199], v[146:147]
	ds_read_b64 v[108:109], v236 offset:46000
	v_fma_f32 v61, v198, v203, v61
	v_fma_f32 v198, v63, v107, v58
	ds_read_b96 v[58:60], v236 offset:46288
	v_pk_mul_f32 v[106:107], v[62:63], v[196:197]
	v_pk_mul_f32 v[116:117], v[62:63], v[116:117]
	ds_bpermute_b32 v62, v237, v198
	v_add_f32_e32 v68, v68, v106
	v_add_f32_e32 v68, v68, v107
	s_waitcnt lgkmcnt(1)
	v_and_b32_e32 v107, 0xffff0000, v59
	v_lshlrev_b32_e32 v106, 16, v59
	v_add_f32_e32 v59, v61, v116
	v_add_f32_e32 v56, v56, v146
	v_fmac_f32_e32 v205, v199, v241
	v_add_f32_e32 v61, v59, v117
	v_mov_b32_e32 v116, v63
	s_waitcnt lgkmcnt(0)
	v_cndmask_b32_e64 v117, v62, v198, s[0:1]
	v_add_f32_e32 v56, v56, v147
	v_fmac_f32_e32 v205, v63, v243
	v_and_b32_e32 v145, 0xffff0000, v103
	v_fma_f32 v56, v116, v94, v56
	v_fma_f32 v63, v117, v95, v56
	ds_bpermute_b32 v62, v237, v63
	v_lshlrev_b32_e32 v144, 16, v103
	v_and_b32_e32 v103, 0xffff0000, v83
	v_lshlrev_b32_e32 v102, 16, v83
	v_pk_mul_f32 v[146:147], v[116:117], v[152:153]
	v_pk_mul_f32 v[150:151], v[116:117], v[150:151]
	v_pk_mul_f32 v[118:119], v[116:117], v[118:119]
	v_mov_b32_e32 v116, v117
	s_waitcnt lgkmcnt(0)
	v_cndmask_b32_e64 v117, v63, v62, s[0:1]
	v_add_f32_e32 v56, v72, v146
	v_add_f32_e32 v72, v99, v150
	v_fma_f32 v62, v116, v102, v68
	v_add_f32_e32 v99, v72, v151
	v_fma_f32 v72, v117, v103, v62
	ds_bpermute_b32 v62, v237, v72
	v_fmac_f32_e32 v110, v199, v239
	v_add_f32_e32 v94, v110, v118
	v_add_f32_e32 v94, v94, v119
	v_mov_b32_e32 v118, v117
	s_waitcnt lgkmcnt(0)
	v_cndmask_b32_e64 v119, v72, v62, s[0:1]
	v_add_f32_e32 v56, v56, v147
	v_pk_mul_f32 v[146:147], v[116:117], v[148:149]
	v_pk_mul_f32 v[144:145], v[116:117], v[144:145]
	v_pk_mul_f32 v[102:103], v[116:117], v[120:121]
	v_add_f32_e32 v68, v198, v146
	v_fma_f32 v56, v118, v142, v56
	v_add_f32_e32 v62, v68, v147
	v_fma_f32 v68, v119, v143, v56
	ds_bpermute_b32 v56, v237, v68
	v_and_b32_e32 v135, 0xffff0000, v97
	v_lshlrev_b32_e32 v134, 16, v97
	v_and_b32_e32 v97, 0xffff0000, v96
	v_lshlrev_b32_e32 v96, 16, v96
	s_waitcnt lgkmcnt(0)
	v_cndmask_b32_e64 v121, v68, v56, s[0:1]
	v_mov_b32_e32 v120, v119
	v_pk_mul_f32 v[96:97], v[118:119], v[96:97]
	v_pk_mul_f32 v[116:117], v[118:119], v[140:141]
	v_add_f32_e32 v102, v205, v102
	v_fma_f32 v56, v120, v138, v62
	v_fma_f32 v62, v121, v139, v56
	ds_bpermute_b32 v56, v237, v62
	v_and_b32_e32 v133, 0xffff0000, v105
	v_lshlrev_b32_e32 v132, 16, v105
	v_and_b32_e32 v105, 0xffff0000, v104
	v_lshlrev_b32_e32 v104, 16, v104
	v_add_f32_e32 v96, v99, v96
	v_add_f32_e32 v99, v102, v103
	s_waitcnt lgkmcnt(0)
	v_cndmask_b32_e64 v103, v62, v56, s[0:1]
	v_mov_b32_e32 v102, v121
	v_and_b32_e32 v115, 0xffff0000, v109
	v_lshlrev_b32_e32 v114, 16, v109
	v_add_f32_e32 v109, v96, v97
	v_pk_mul_f32 v[96:97], v[120:121], v[104:105]
	v_add_f32_e32 v61, v61, v144
	v_fma_f32 v56, v102, v134, v109
	v_fma_f32 v56, v103, v135, v56
	ds_bpermute_b32 v109, v237, v56
	v_add_f32_e32 v61, v61, v145
	v_add_f32_e32 v61, v61, v96
	v_add_f32_e32 v94, v94, v116
	v_add_f32_e32 v61, v61, v97
	s_waitcnt lgkmcnt(0)
	v_cndmask_b32_e64 v97, v109, v56, s[0:1]
	v_mov_b32_e32 v96, v103
	v_add_f32_e32 v94, v94, v117
	v_fma_f32 v61, v96, v132, v61
	v_fma_f32 v61, v97, v133, v61
	ds_bpermute_b32 v109, v237, v61
	v_fma_f32 v94, v102, v136, v94
	v_and_b32_e32 v59, 0xffff0000, v58
	v_lshlrev_b32_e32 v58, 16, v58
	v_fma_f32 v94, v103, v137, v94
	s_waitcnt lgkmcnt(0)
	v_cndmask_b32_e64 v103, v109, v61, s[0:1]
	v_mov_b32_e32 v102, v97
	v_fma_f32 v58, v102, v58, v94
	v_fma_f32 v99, v120, v122, v99
	v_fma_f32 v104, v103, v59, v58
	ds_bpermute_b32 v94, v237, v104
	v_fma_f32 v99, v121, v123, v99
	v_and_b32_e32 v95, 0xffff0000, v108
	v_fma_f32 v58, v96, v124, v99
	v_fma_f32 v99, v97, v125, v58
	s_waitcnt lgkmcnt(0)
	v_cndmask_b32_e64 v59, v94, v104, s[0:1]
	v_mov_b32_e32 v58, v103
	ds_read_b64 v[82:83], v236 offset:55654
	v_fma_f32 v94, v58, v126, v99
	v_fma_f32 v99, v59, v127, v94
	ds_bpermute_b32 v96, v237, v99
	v_lshlrev_b32_e32 v94, 16, v108
	v_cndmask_b32_e64 v144, v101, v8, s[0:1]
	v_fma_f32 v56, v102, v94, v56
	v_fma_f32 v56, v103, v95, v56
	s_waitcnt lgkmcnt(0)
	v_cndmask_b32_e64 v95, v96, v99, s[0:1]
	v_mov_b32_e32 v94, v59
	v_fma_f32 v56, v94, v114, v56
	v_fma_f32 v96, v95, v115, v56
	ds_bpermute_b32 v56, v237, v96
	v_fma_f32 v58, v58, v130, v61
	v_mov_b32_e32 v102, v95
	v_fma_f32 v61, v59, v131, v58
	v_pk_mul_f32 v[58:59], v[94:95], v[106:107]
	s_waitcnt lgkmcnt(0)
	v_cndmask_b32_e64 v103, v96, v56, s[0:1]
	v_add_f32_e32 v58, v104, v58
	v_fma_f32 v56, v102, v128, v61
	v_fma_f32 v95, v103, v129, v56
	ds_bpermute_b32 v56, v237, v95
	v_add_f32_e32 v94, v58, v59
	v_and_b32_e32 v59, 0xffff0000, v60
	v_lshlrev_b32_e32 v58, 16, v60
	v_mov_b32_e32 v60, v103
	s_waitcnt lgkmcnt(0)
	v_cndmask_b32_e64 v61, v95, v56, s[0:1]
	ds_read_b64 v[104:105], v236 offset:55362
	v_fma_f32 v56, v60, v58, v94
	v_fma_f32 v94, v61, v59, v56
	ds_bpermute_b32 v60, v237, v94
	v_and_b32_e32 v57, 0xffff0000, v82
	v_fma_f32 v58, v102, v112, v99
	v_lshlrev_b32_e32 v56, 16, v82
	v_fma_f32 v82, v103, v113, v58
	s_waitcnt lgkmcnt(0)
	v_cndmask_b32_e64 v59, v94, v60, s[0:1]
	v_and_b32_e32 v103, 0xffff0000, v111
	v_lshlrev_b32_e32 v102, 16, v111
	v_mov_b32_e32 v58, v61
	v_pk_mul_f32 v[60:61], v[58:59], v[102:103]
	v_and_b32_e32 v117, 0xffff0000, v104
	v_add_f32_e32 v82, v82, v60
	ds_read_b96 v[58:60], v236 offset:55504
	v_lshlrev_b32_e32 v116, 16, v104
	ds_read_b96 v[102:104], v236 offset:54482
	v_and_b32_e32 v139, 0xffff0000, v69
	v_lshlrev_b32_e32 v138, 16, v69
	v_fma_f32 v69, v144, v200, v9
	ds_read_b64 v[128:129], v236 offset:54194
	ds_read_b64 v[134:135], v236 offset:54048
	ds_bpermute_b32 v9, v237, v69
	ds_read_b64 v[108:109], v236 offset:55216
	v_and_b32_e32 v111, 0xffff0000, v105
	v_lshlrev_b32_e32 v110, 16, v105
	s_waitcnt lgkmcnt(4)
	v_and_b32_e32 v125, 0xffff0000, v104
	v_lshlrev_b32_e32 v124, 16, v104
	ds_read_b96 v[104:106], v236 offset:54336
	s_waitcnt lgkmcnt(3)
	v_and_b32_e32 v141, 0xffff0000, v135
	v_lshlrev_b32_e32 v140, 16, v135
	v_and_b32_e32 v135, 0xffff0000, v134
	v_lshlrev_b32_e32 v134, 16, v134
	s_waitcnt lgkmcnt(2)
	v_cndmask_b32_e64 v145, v9, v69, s[0:1]
	s_waitcnt lgkmcnt(0)
	v_and_b32_e32 v143, 0xffff0000, v105
	v_lshlrev_b32_e32 v142, 16, v105
	v_and_b32_e32 v105, 0xffff0000, v104
	v_lshlrev_b32_e32 v104, 16, v104
	v_and_b32_e32 v121, 0xffff0000, v71
	v_lshlrev_b32_e32 v120, 16, v71
	v_and_b32_e32 v131, 0xffff0000, v70
	v_lshlrev_b32_e32 v130, 16, v70
	v_and_b32_e32 v71, 0xffff0000, v73
	v_lshlrev_b32_e32 v70, 16, v73
	v_fma_f32 v73, v144, v134, v8
	v_and_b32_e32 v137, 0xffff0000, v103
	v_fma_f32 v8, v144, v104, v10
	v_fma_f32 v104, v145, v105, v8
	ds_bpermute_b32 v10, v237, v104
	v_lshlrev_b32_e32 v136, 16, v103
	v_and_b32_e32 v103, 0xffff0000, v102
	v_lshlrev_b32_e32 v102, 16, v102
	v_fma_f32 v97, v144, v202, v11
	s_waitcnt lgkmcnt(0)
	v_cndmask_b32_e64 v11, v10, v104, s[0:1]
	v_mov_b32_e32 v10, v145
	v_fma_f32 v101, v144, v206, v14
	v_fma_f32 v105, v144, v238, v15
	v_and_b32_e32 v133, 0xffff0000, v129
	v_fma_f32 v14, v10, v102, v97
	v_fma_f32 v97, v11, v103, v14
	ds_bpermute_b32 v14, v237, v97
	v_lshlrev_b32_e32 v132, 16, v129
	v_and_b32_e32 v129, 0xffff0000, v128
	v_lshlrev_b32_e32 v128, 16, v128
	v_fma_f32 v99, v144, v204, v13
	v_fma_f32 v8, v144, v92, v12
	s_waitcnt lgkmcnt(0)
	v_cndmask_b32_e64 v15, v14, v97, s[0:1]
	v_mov_b32_e32 v14, v11
	v_fma_f32 v73, v145, v135, v73
	v_fma_f32 v12, v10, v128, v69
	v_fma_f32 v69, v145, v93, v8
	v_pk_mul_f32 v[8:9], v[10:11], v[90:91]
	v_pk_mul_f32 v[92:93], v[14:15], v[138:139]
	v_fma_f32 v10, v14, v140, v73
	v_add_f32_e32 v90, v69, v92
	v_fma_f32 v69, v15, v141, v10
	ds_bpermute_b32 v10, v237, v69
	v_fmac_f32_e32 v105, v145, v242
	v_add_f32_e32 v8, v99, v8
	v_fmac_f32_e32 v105, v11, v244
	v_fma_f32 v73, v11, v129, v12
	s_waitcnt lgkmcnt(0)
	v_cndmask_b32_e64 v11, v69, v10, s[0:1]
	v_mov_b32_e32 v10, v15
	v_pk_mul_f32 v[12:13], v[14:15], v[142:143]
	v_add_f32_e32 v91, v8, v9
	v_pk_mul_f32 v[8:9], v[14:15], v[88:89]
	v_pk_mul_f32 v[88:89], v[10:11], v[70:71]
	v_fma_f32 v14, v10, v132, v73
	v_fma_f32 v70, v11, v133, v14
	ds_bpermute_b32 v14, v237, v70
	v_fmac_f32_e32 v101, v145, v240
	v_and_b32_e32 v123, 0xffff0000, v67
	v_lshlrev_b32_e32 v122, 16, v67
	v_and_b32_e32 v127, 0xffff0000, v66
	v_lshlrev_b32_e32 v126, 16, v66
	v_and_b32_e32 v67, 0xffff0000, v106
	v_lshlrev_b32_e32 v66, 16, v106
	v_add_f32_e32 v12, v104, v12
	v_add_f32_e32 v8, v101, v8
	s_waitcnt lgkmcnt(0)
	v_cndmask_b32_e64 v15, v70, v14, s[0:1]
	v_mov_b32_e32 v14, v11
	v_add_f32_e32 v73, v12, v13
	v_pk_mul_f32 v[12:13], v[10:11], v[136:137]
	v_add_f32_e32 v71, v91, v88
	v_add_f32_e32 v88, v8, v9
	v_pk_mul_f32 v[8:9], v[10:11], v[86:87]
	v_add_f32_e32 v12, v97, v12
	v_fma_f32 v10, v14, v66, v73
	v_fma_f32 v67, v15, v67, v10
	ds_bpermute_b32 v73, v237, v67
	v_mov_b32_e32 v86, v15
	v_add_f32_e32 v66, v12, v13
	v_pk_mul_f32 v[10:11], v[14:15], v[130:131]
	v_pk_mul_f32 v[12:13], v[14:15], v[126:127]
	s_waitcnt lgkmcnt(0)
	v_cndmask_b32_e64 v87, v67, v73, s[0:1]
	v_add_f32_e32 v90, v90, v93
	v_fma_f32 v14, v86, v124, v66
	v_fma_f32 v66, v87, v125, v14
	ds_bpermute_b32 v14, v237, v66
	v_add_f32_e32 v10, v90, v10
	v_add_f32_e32 v12, v88, v12
	v_add_f32_e32 v88, v10, v11
	v_mov_b32_e32 v10, v87
	s_waitcnt lgkmcnt(0)
	v_cndmask_b32_e64 v11, v66, v14, s[0:1]
	v_and_b32_e32 v119, 0xffff0000, v75
	v_lshlrev_b32_e32 v118, 16, v75
	v_and_b32_e32 v75, 0xffff0000, v74
	v_lshlrev_b32_e32 v74, 16, v74
	v_add_f32_e32 v8, v105, v8
	v_fma_f32 v14, v10, v120, v88
	v_add_f32_e32 v73, v8, v9
	v_pk_mul_f32 v[8:9], v[86:87], v[74:75]
	v_fma_f32 v74, v11, v121, v14
	ds_bpermute_b32 v14, v237, v74
	v_add_f32_e32 v71, v71, v89
	v_add_f32_e32 v8, v71, v8
	v_add_f32_e32 v75, v8, v9
	v_mov_b32_e32 v8, v11
	s_waitcnt lgkmcnt(0)
	v_cndmask_b32_e64 v9, v14, v74, s[0:1]
	v_add_f32_e32 v71, v12, v13
	v_fma_f32 v14, v8, v118, v75
	v_fma_f32 v75, v9, v119, v14
	ds_bpermute_b32 v14, v237, v75
	v_and_b32_e32 v115, 0xffff0000, v59
	v_fma_f32 v10, v10, v122, v71
	v_lshlrev_b32_e32 v114, 16, v59
	v_and_b32_e32 v59, 0xffff0000, v58
	v_lshlrev_b32_e32 v58, 16, v58
	v_fma_f32 v71, v11, v123, v10
	s_waitcnt lgkmcnt(0)
	v_cndmask_b32_e64 v11, v14, v75, s[0:1]
	v_mov_b32_e32 v10, v9
	v_fma_f32 v14, v10, v58, v71
	v_fma_f32 v14, v11, v59, v14
	ds_bpermute_b32 v15, v237, v14
	v_fma_f32 v12, v86, v84, v73
	v_fma_f32 v12, v87, v85, v12
	v_and_b32_e32 v107, 0xffff0000, v108
	v_fma_f32 v8, v8, v64, v12
	v_fma_f32 v58, v9, v65, v8
	s_waitcnt lgkmcnt(0)
	v_cndmask_b32_e64 v9, v15, v14, s[0:1]
	v_mov_b32_e32 v8, v11
	v_lshlrev_b32_e32 v106, 16, v108
	v_fma_f32 v12, v8, v80, v58
	v_fma_f32 v58, v9, v81, v12
	ds_bpermute_b32 v12, v237, v58
	v_and_b32_e32 v113, 0xffff0000, v109
	v_fma_f32 v10, v10, v106, v74
	v_lshlrev_b32_e32 v112, 16, v109
	v_fma_f32 v15, v11, v107, v10
	s_waitcnt lgkmcnt(0)
	v_cndmask_b32_e64 v11, v12, v58, s[0:1]
	v_mov_b32_e32 v10, v9
	v_fma_f32 v12, v10, v112, v15
	v_fma_f32 v74, v11, v113, v12
	ds_bpermute_b32 v12, v237, v74
	v_fma_f32 v8, v8, v116, v75
	v_fma_f32 v15, v9, v117, v8
	v_pk_mul_f32 v[8:9], v[10:11], v[114:115]
	v_add_f32_e32 v64, v82, v61
	s_waitcnt lgkmcnt(0)
	v_cndmask_b32_e64 v13, v74, v12, s[0:1]
	v_mov_b32_e32 v12, v11
	v_add_f32_e32 v8, v14, v8
	v_fma_f32 v10, v12, v110, v15
	v_fma_f32 v71, v13, v111, v10
	ds_bpermute_b32 v10, v237, v71
	v_add_f32_e32 v11, v8, v9
	v_and_b32_e32 v9, 0xffff0000, v60
	v_lshlrev_b32_e32 v8, 16, v60
	v_mov_b32_e32 v14, v13
	s_waitcnt lgkmcnt(0)
	v_cndmask_b32_e64 v15, v71, v10, s[0:1]
	v_and_b32_e32 v81, 0xffff0000, v83
	v_fma_f32 v8, v14, v8, v11
	v_fma_f32 v65, v15, v9, v8
	ds_bpermute_b32 v10, v237, v65
	v_lshlrev_b32_e32 v80, 16, v83
	v_fma_f32 v8, v12, v56, v58
	v_fma_f32 v73, v13, v57, v8
	s_waitcnt lgkmcnt(0)
	v_cndmask_b32_e64 v61, v65, v10, s[0:1]
	ds_read2_b64 v[8:11], v100 offset0:4 offset1:6
	ds_read2_b64 v[56:59], v98 offset0:132 offset1:134
	v_mov_b32_e32 v60, v15
	v_cvt_pk_bf16_f32 v12, v63, v72
	v_cvt_pk_bf16_f32 v13, v68, v62
	v_cvt_pk_bf16_f32 v14, v96, v95
	v_cvt_pk_bf16_f32 v15, v94, v64
	s_ashr_i32 s9, s8, 31
	s_lshl_b64 s[2:3], s[8:9], 6
	s_waitcnt lgkmcnt(1)
	v_mfma_f32_32x32x16_bf16 v[32:47], v[8:11], v[12:15], v[32:47]
	v_mul_f32_e64 v8, v60, v80
	v_mul_f32_e64 v9, v61, v81
	v_cvt_pk_bf16_f32 v10, v74, v71
	v_add_f32_e32 v8, v73, v8
	v_add_f32_e32 v73, v8, v9
	v_cvt_pk_bf16_f32 v8, v69, v70
	v_cvt_pk_bf16_f32 v9, v67, v66
	v_cvt_pk_bf16_f32 v11, v65, v73
	s_nop 3
	ds_bpermute_b32 v75, v237, v32
	v_cndmask_b32_e64 v0, -v0, v0, vcc
	s_waitcnt lgkmcnt(1)
	v_mfma_f32_32x32x16_bf16 v[16:31], v[56:59], v[8:11], v[16:31]
	ds_read_u16 v8, v236 offset:47312
	ds_read_u16 v9, v236 offset:56528
	ds_read_u16 v10, v236 offset:47600
	ds_read_u16 v11, v236 offset:56816
	ds_read_u16 v12, v236 offset:48464
	s_waitcnt lgkmcnt(4)
	v_lshlrev_b32_e32 v99, 16, v8
	s_waitcnt lgkmcnt(3)
	v_lshlrev_b32_e32 v101, 16, v9
	s_waitcnt lgkmcnt(2)
	v_lshlrev_b32_e32 v150, 16, v10
	s_waitcnt lgkmcnt(1)
	v_lshlrev_b32_e32 v151, 16, v11
	s_waitcnt lgkmcnt(0)
	v_lshlrev_b32_e32 v152, 16, v12
	ds_read_u16 v12, v236 offset:57680
	ds_read_b128 v[58:61], v236 offset:48608
	ds_read_b128 v[8:11], v236 offset:57824
	ds_read_b32 v13, v236 offset:48752
	ds_read_b32 v14, v236 offset:57968
	s_waitcnt lgkmcnt(4)
	v_lshlrev_b32_e32 v153, 16, v12
	s_waitcnt lgkmcnt(3)
	v_lshlrev_b32_e32 v196, 16, v58
	s_waitcnt lgkmcnt(2)
	v_lshlrev_b32_e32 v197, 16, v8
	s_waitcnt lgkmcnt(1)
	v_lshlrev_b32_e32 v198, 16, v13
	v_and_b32_e32 v201, 0xffff0000, v8
	v_and_b32_e32 v8, 0xffff0000, v13
	ds_read_u16 v12, v236 offset:48756
	ds_read_u16 v13, v236 offset:57972
	ds_read_b128 v[80:83], v236 offset:48320
	ds_read_b128 v[88:91], v236 offset:48758
	ds_read_b128 v[102:105], v236 offset:57974
	s_waitcnt lgkmcnt(5)
	v_lshlrev_b32_e32 v199, 16, v14
	v_and_b32_e32 v200, 0xffff0000, v58
	v_and_b32_e32 v202, 0xffff0000, v14
	s_waitcnt lgkmcnt(1)
	v_and_b32_e32 v113, 0xffff0000, v88
	v_lshlrev_b32_e32 v112, 16, v88
	v_and_b32_e32 v115, 0xffff0000, v89
	v_lshlrev_b32_e32 v114, 16, v89
	ds_read_b64 v[88:89], v236 offset:48482
	v_lshlrev_b32_e32 v203, 16, v12
	v_lshlrev_b32_e32 v204, 16, v13
	v_and_b32_e32 v111, 0xffff0000, v59
	v_lshlrev_b32_e32 v110, 16, v59
	s_waitcnt lgkmcnt(1)
	v_and_b32_e32 v59, 0xffff0000, v102
	v_lshlrev_b32_e32 v58, 16, v102
	v_and_b32_e32 v57, 0xffff0000, v103
	v_lshlrev_b32_e32 v56, 16, v103
	v_and_b32_e32 v103, 0xffff0000, v90
	v_lshlrev_b32_e32 v102, 16, v90
	v_and_b32_e32 v15, 0xffff0000, v104
	v_lshlrev_b32_e32 v14, 16, v104
	v_and_b32_e32 v13, 0xffff0000, v105
	v_lshlrev_b32_e32 v12, 16, v105
	s_waitcnt lgkmcnt(0)
	v_and_b32_e32 v105, 0xffff0000, v89
	v_lshlrev_b32_e32 v104, 16, v89
	v_and_b32_e32 v119, 0xffff0000, v88
	v_lshlrev_b32_e32 v118, 16, v88
	ds_read_b96 v[88:90], v236 offset:47602
	v_cndmask_b32_e64 v146, v75, v32, s[0:1]
	v_fma_f32 v75, v146, v99, v33
	ds_read_b128 v[84:87], v236 offset:48466
	v_and_b32_e32 v123, 0xffff0000, v83
	v_lshlrev_b32_e32 v122, 16, v83
	v_and_b32_e32 v125, 0xffff0000, v61
	v_lshlrev_b32_e32 v124, 16, v61
	v_and_b32_e32 v131, 0xffff0000, v60
	v_lshlrev_b32_e32 v130, 16, v60
	ds_read_b64 v[60:61], v236 offset:47314
	v_and_b32_e32 v133, 0xffff0000, v82
	v_lshlrev_b32_e32 v132, 16, v82
	ds_read_b64 v[82:83], v236 offset:47168
	ds_bpermute_b32 v33, v237, v75
	v_and_b32_e32 v117, 0xffff0000, v91
	v_lshlrev_b32_e32 v116, 16, v91
	s_waitcnt lgkmcnt(4)
	v_and_b32_e32 v127, 0xffff0000, v90
	v_lshlrev_b32_e32 v126, 16, v90
	ds_read_b96 v[90:92], v236 offset:47456
	v_and_b32_e32 v107, 0xffff0000, v80
	v_lshlrev_b32_e32 v106, 16, v80
	s_waitcnt lgkmcnt(4)
	v_and_b32_e32 v121, 0xffff0000, v87
	v_lshlrev_b32_e32 v120, 16, v87
	v_and_b32_e32 v129, 0xffff0000, v86
	v_lshlrev_b32_e32 v128, 16, v86
	v_and_b32_e32 v141, 0xffff0000, v81
	v_lshlrev_b32_e32 v140, 16, v81
	s_waitcnt lgkmcnt(2)
	v_and_b32_e32 v143, 0xffff0000, v83
	v_lshlrev_b32_e32 v142, 16, v83
	v_and_b32_e32 v87, 0xffff0000, v82
	v_lshlrev_b32_e32 v86, 16, v82
	ds_read_b128 v[80:83], v236 offset:57536
	s_waitcnt lgkmcnt(2)
	v_cndmask_b32_e64 v147, v33, v75, s[0:1]
	v_and_b32_e32 v109, 0xffff0000, v84
	v_lshlrev_b32_e32 v108, 16, v84
	v_and_b32_e32 v135, 0xffff0000, v85
	v_lshlrev_b32_e32 v134, 16, v85
	s_waitcnt lgkmcnt(1)
	v_and_b32_e32 v85, 0xffff0000, v90
	v_lshlrev_b32_e32 v84, 16, v90
	v_fma_f32 v32, v146, v86, v32
	v_fma_f32 v99, v147, v87, v32
	v_pk_mul_f32 v[32:33], v[146:147], v[84:85]
	ds_read_b128 v[84:87], v236 offset:57682
	v_add_f32_e32 v32, v34, v32
	s_waitcnt lgkmcnt(1)
	v_and_b32_e32 v149, 0xffff0000, v80
	v_lshlrev_b32_e32 v148, 16, v80
	v_fma_f32 v80, v146, v196, v38
	v_fma_f32 v196, v146, v198, v39
	v_add_f32_e32 v198, v32, v33
	ds_bpermute_b32 v33, v237, v198
	v_and_b32_e32 v139, 0xffff0000, v89
	v_fma_f32 v32, v146, v106, v36
	v_lshlrev_b32_e32 v138, 16, v89
	v_and_b32_e32 v89, 0xffff0000, v88
	v_lshlrev_b32_e32 v88, 16, v88
	v_fma_f32 v205, v147, v107, v32
	v_mov_b32_e32 v32, v147
	s_waitcnt lgkmcnt(0)
	v_cndmask_b32_e64 v33, v33, v198, s[0:1]
	v_fmac_f32_e32 v196, v147, v8
	v_fma_f32 v8, v146, v150, v35
	v_and_b32_e32 v137, 0xffff0000, v61
	v_fma_f32 v8, v32, v88, v8
	v_fma_f32 v150, v33, v89, v8
	ds_bpermute_b32 v8, v237, v150
	v_lshlrev_b32_e32 v136, 16, v61
	v_and_b32_e32 v61, 0xffff0000, v60
	v_lshlrev_b32_e32 v60, 16, v60
	v_fma_f32 v90, v146, v152, v37
	v_pk_mul_f32 v[36:37], v[32:33], v[108:109]
	s_waitcnt lgkmcnt(0)
	v_cndmask_b32_e64 v39, v8, v150, s[0:1]
	v_fma_f32 v8, v32, v60, v75
	v_fmac_f32_e32 v196, v33, v203
	v_mov_b32_e32 v38, v33
	v_fma_f32 v33, v33, v61, v8
	v_add_f32_e32 v8, v90, v36
	v_and_b32_e32 v109, 0xffff0000, v9
	v_lshlrev_b32_e32 v108, 16, v9
	v_add_f32_e32 v60, v8, v37
	v_pk_mul_f32 v[106:107], v[38:39], v[140:141]
	v_fma_f32 v8, v38, v142, v99
	v_fma_f32 v32, v39, v143, v8
	ds_bpermute_b32 v36, v237, v32
	v_mov_b32_e32 v140, v39
	v_and_b32_e32 v145, 0xffff0000, v91
	v_lshlrev_b32_e32 v144, 16, v91
	s_waitcnt lgkmcnt(0)
	v_cndmask_b32_e64 v141, v32, v36, s[0:1]
	v_and_b32_e32 v93, 0xffff0000, v92
	v_fma_f32 v33, v140, v136, v33
	v_fma_f32 v33, v141, v137, v33
	ds_bpermute_b32 v36, v237, v33
	v_lshlrev_b32_e32 v92, 16, v92
	v_fma_f32 v34, v38, v144, v198
	v_mov_b32_e32 v142, v141
	v_fma_f32 v37, v39, v145, v34
	s_waitcnt lgkmcnt(0)
	v_cndmask_b32_e64 v143, v33, v36, s[0:1]
	v_fmac_f32_e32 v80, v147, v200
	v_fma_f32 v34, v142, v92, v37
	v_pk_mul_f32 v[110:111], v[38:39], v[110:111]
	v_fma_f32 v34, v143, v93, v34
	v_add_f32_e32 v39, v80, v110
	ds_bpermute_b32 v80, v237, v34
	ds_read_b64 v[88:89], v236 offset:48774
	ds_read_b64 v[8:9], v236 offset:57990
	v_add_f32_e32 v39, v39, v111
	v_fma_f32 v60, v140, v134, v60
	v_add_f32_e32 v35, v205, v106
	v_fma_f32 v75, v140, v138, v150
	v_fma_f32 v60, v141, v135, v60
	s_waitcnt lgkmcnt(2)
	v_cndmask_b32_e64 v135, v34, v80, s[0:1]
	v_mov_b32_e32 v134, v143
	v_and_b32_e32 v147, 0xffff0000, v84
	v_lshlrev_b32_e32 v146, 16, v84
	v_add_f32_e32 v35, v35, v107
	v_fma_f32 v75, v141, v139, v75
	v_fma_f32 v84, v140, v112, v196
	v_fma_f32 v80, v141, v113, v84
	v_pk_mul_f32 v[112:113], v[134:135], v[128:129]
	ds_read_b64 v[128:129], v236 offset:56530
	s_waitcnt lgkmcnt(2)
	v_and_b32_e32 v91, 0xffff0000, v88
	v_lshlrev_b32_e32 v90, 16, v88
	v_fma_f32 v88, v142, v132, v35
	v_fma_f32 v35, v134, v126, v75
	v_fma_f32 v35, v135, v127, v35
	ds_bpermute_b32 v75, v237, v35
	v_mov_b32_e32 v126, v135
	v_fma_f32 v84, v143, v133, v88
	v_add_f32_e32 v60, v60, v112
	v_add_f32_e32 v60, v60, v113
	s_waitcnt lgkmcnt(0)
	v_cndmask_b32_e64 v127, v35, v75, s[0:1]
	v_mov_b32_e32 v112, v127
	v_fma_f32 v75, v126, v122, v84
	v_fma_f32 v75, v127, v123, v75
	ds_bpermute_b32 v84, v237, v75
	ds_read_b64 v[136:137], v236 offset:48336
	ds_read_b96 v[36:38], v236 offset:48624
	s_waitcnt lgkmcnt(2)
	v_cndmask_b32_e64 v113, v84, v75, s[0:1]
	v_fma_f32 v39, v142, v130, v39
	v_fma_f32 v60, v112, v120, v60
	v_fma_f32 v60, v113, v121, v60
	ds_bpermute_b32 v84, v237, v60
	v_fma_f32 v39, v143, v131, v39
	s_waitcnt lgkmcnt(1)
	v_and_b32_e32 v107, 0xffff0000, v37
	v_fma_f32 v39, v126, v124, v39
	v_lshlrev_b32_e32 v106, 16, v37
	v_and_b32_e32 v37, 0xffff0000, v36
	v_lshlrev_b32_e32 v36, 16, v36
	v_fma_f32 v39, v127, v125, v39
	s_waitcnt lgkmcnt(0)
	v_cndmask_b32_e64 v121, v84, v60, s[0:1]
	v_mov_b32_e32 v120, v113
	v_fma_f32 v80, v134, v114, v80
	v_fma_f32 v36, v120, v36, v39
	v_fma_f32 v39, v121, v37, v36
	ds_bpermute_b32 v84, v237, v39
	v_fma_f32 v80, v135, v115, v80
	v_pk_mul_f32 v[36:37], v[112:113], v[102:103]
	v_mov_b32_e32 v102, v121
	v_add_f32_e32 v36, v80, v36
	s_waitcnt lgkmcnt(0)
	v_cndmask_b32_e64 v103, v84, v39, s[0:1]
	v_add_f32_e32 v80, v36, v37
	v_and_b32_e32 v111, 0xffff0000, v136
	v_fma_f32 v36, v102, v116, v80
	v_fma_f32 v80, v103, v117, v36
	ds_bpermute_b32 v84, v237, v80
	v_lshlrev_b32_e32 v110, 16, v136
	v_pk_mul_f32 v[36:37], v[120:121], v[110:111]
	v_and_b32_e32 v93, 0xffff0000, v137
	v_lshlrev_b32_e32 v92, 16, v137
	v_add_f32_e32 v36, v75, v36
	s_waitcnt lgkmcnt(0)
	v_cndmask_b32_e64 v111, v84, v80, s[0:1]
	v_mov_b32_e32 v110, v103
	v_add_f32_e32 v75, v36, v37
	v_pk_mul_f32 v[36:37], v[110:111], v[92:93]
	v_add_f32_e32 v36, v75, v36
	v_add_f32_e32 v36, v36, v37
	ds_bpermute_b32 v37, v237, v36
	v_fma_f32 v60, v102, v118, v60
	v_mov_b32_e32 v102, v111
	v_fma_f32 v60, v103, v119, v60
	s_waitcnt lgkmcnt(0)
	v_cndmask_b32_e64 v103, v36, v37, s[0:1]
	v_fma_f32 v39, v110, v106, v39
	v_fma_f32 v37, v102, v104, v60
	v_fma_f32 v37, v103, v105, v37
	ds_bpermute_b32 v60, v237, v37
	v_fma_f32 v75, v111, v107, v39
	v_and_b32_e32 v39, 0xffff0000, v38
	v_lshlrev_b32_e32 v38, 16, v38
	v_mov_b32_e32 v92, v103
	s_waitcnt lgkmcnt(0)
	v_cndmask_b32_e64 v93, v37, v60, s[0:1]
	v_fma_f32 v38, v92, v38, v75
	v_fma_f32 v38, v93, v39, v38
	ds_bpermute_b32 v39, v237, v38
	ds_bpermute_b32 v97, v237, v16
	v_and_b32_e32 v61, 0xffff0000, v8
	v_lshlrev_b32_e32 v60, 16, v8
	v_fma_f32 v8, v102, v90, v80
	v_fma_f32 v8, v103, v91, v8
	s_waitcnt lgkmcnt(1)
	v_cndmask_b32_e64 v91, v38, v39, s[0:1]
	v_and_b32_e32 v103, 0xffff0000, v89
	v_lshlrev_b32_e32 v102, 16, v89
	v_mov_b32_e32 v90, v93
	v_pk_mul_f32 v[90:91], v[90:91], v[102:103]
	ds_read_b64 v[110:111], v236 offset:57552
	ds_read_b96 v[102:104], v236 offset:56818
	s_waitcnt lgkmcnt(2)
	v_cndmask_b32_e64 v140, v97, v16, s[0:1]
	v_fma_f32 v39, v140, v101, v17
	ds_read_b64 v[132:133], v236 offset:56384
	ds_bpermute_b32 v17, v237, v39
	s_waitcnt lgkmcnt(2)
	v_and_b32_e32 v125, 0xffff0000, v104
	v_lshlrev_b32_e32 v124, 16, v104
	ds_read_b96 v[104:106], v236 offset:56672
	v_and_b32_e32 v137, 0xffff0000, v81
	v_lshlrev_b32_e32 v136, 16, v81
	s_waitcnt lgkmcnt(2)
	v_and_b32_e32 v81, 0xffff0000, v133
	v_lshlrev_b32_e32 v80, 16, v133
	v_and_b32_e32 v133, 0xffff0000, v132
	v_lshlrev_b32_e32 v132, 16, v132
	s_waitcnt lgkmcnt(1)
	v_cndmask_b32_e64 v141, v17, v39, s[0:1]
	s_waitcnt lgkmcnt(0)
	v_and_b32_e32 v139, 0xffff0000, v105
	v_lshlrev_b32_e32 v138, 16, v105
	v_and_b32_e32 v105, 0xffff0000, v104
	v_lshlrev_b32_e32 v104, 16, v104
	v_pk_mul_f32 v[132:133], v[140:141], v[132:133]
	v_and_b32_e32 v135, 0xffff0000, v103
	v_add_f32_e32 v75, v16, v132
	v_lshlrev_b32_e32 v134, 16, v103
	v_fma_f32 v16, v140, v104, v18
	v_fma_f32 v104, v141, v105, v16
	ds_bpermute_b32 v18, v237, v104
	v_and_b32_e32 v103, 0xffff0000, v102
	v_lshlrev_b32_e32 v102, 16, v102
	v_fma_f32 v97, v140, v151, v19
	v_fma_f32 v101, v140, v197, v22
	s_waitcnt lgkmcnt(0)
	v_cndmask_b32_e64 v19, v18, v104, s[0:1]
	v_mov_b32_e32 v18, v141
	v_fma_f32 v105, v140, v199, v23
	v_and_b32_e32 v131, 0xffff0000, v85
	v_fma_f32 v22, v18, v102, v97
	v_fma_f32 v97, v19, v103, v22
	ds_bpermute_b32 v22, v237, v97
	v_lshlrev_b32_e32 v130, 16, v85
	v_and_b32_e32 v85, 0xffff0000, v129
	v_lshlrev_b32_e32 v84, 16, v129
	v_and_b32_e32 v129, 0xffff0000, v128
	v_lshlrev_b32_e32 v128, 16, v128
	v_fma_f32 v99, v140, v153, v21
	v_fma_f32 v16, v140, v148, v20
	s_waitcnt lgkmcnt(0)
	v_cndmask_b32_e64 v23, v22, v97, s[0:1]
	v_mov_b32_e32 v22, v19
	v_add_f32_e32 v75, v75, v133
	v_fma_f32 v20, v18, v128, v39
	v_fma_f32 v39, v141, v149, v16
	v_fma_f32 v18, v18, v146, v99
	v_fma_f32 v16, v22, v80, v75
	v_fma_f32 v16, v23, v81, v16
	ds_bpermute_b32 v80, v237, v16
	v_fmac_f32_e32 v105, v141, v202
	v_fma_f32 v75, v19, v129, v20
	v_pk_mul_f32 v[20:21], v[22:23], v[138:139]
	v_pk_mul_f32 v[102:103], v[22:23], v[136:137]
	s_waitcnt lgkmcnt(0)
	v_cndmask_b32_e64 v81, v16, v80, s[0:1]
	v_mov_b32_e32 v80, v23
	v_fma_f32 v99, v19, v147, v18
	v_fmac_f32_e32 v105, v19, v204
	v_pk_mul_f32 v[18:19], v[22:23], v[108:109]
	v_add_f32_e32 v20, v104, v20
	v_fma_f32 v17, v80, v84, v75
	v_add_f32_e32 v75, v20, v21
	v_pk_mul_f32 v[20:21], v[80:81], v[134:135]
	v_fma_f32 v17, v81, v85, v17
	v_add_f32_e32 v20, v97, v20
	ds_bpermute_b32 v97, v237, v17
	v_fmac_f32_e32 v101, v141, v201
	v_and_b32_e32 v127, 0xffff0000, v106
	v_lshlrev_b32_e32 v126, 16, v106
	v_add_f32_e32 v18, v101, v18
	v_pk_mul_f32 v[84:85], v[80:81], v[130:131]
	v_pk_mul_f32 v[22:23], v[80:81], v[58:59]
	s_waitcnt lgkmcnt(0)
	v_cndmask_b32_e64 v59, v17, v97, s[0:1]
	v_mov_b32_e32 v58, v81
	v_add_f32_e32 v84, v99, v84
	v_add_f32_e32 v99, v18, v19
	v_and_b32_e32 v121, 0xffff0000, v83
	v_fma_f32 v18, v58, v126, v75
	v_fma_f32 v18, v59, v127, v18
	ds_bpermute_b32 v19, v237, v18
	v_lshlrev_b32_e32 v120, 16, v83
	v_and_b32_e32 v123, 0xffff0000, v11
	v_lshlrev_b32_e32 v122, 16, v11
	v_and_b32_e32 v11, 0xffff0000, v10
	v_lshlrev_b32_e32 v10, 16, v10
	v_and_b32_e32 v83, 0xffff0000, v82
	v_lshlrev_b32_e32 v82, 16, v82
	s_waitcnt lgkmcnt(0)
	v_cndmask_b32_e64 v81, v18, v19, s[0:1]
	v_mov_b32_e32 v80, v59
	v_add_f32_e32 v75, v20, v21
	v_pk_mul_f32 v[20:21], v[58:59], v[82:83]
	v_pk_mul_f32 v[10:11], v[58:59], v[10:11]
	v_add_f32_e32 v39, v39, v102
	v_fma_f32 v19, v80, v124, v75
	v_fma_f32 v19, v81, v125, v19
	ds_bpermute_b32 v58, v237, v19
	v_add_f32_e32 v39, v39, v103
	v_add_f32_e32 v22, v105, v22
	v_add_f32_e32 v20, v39, v20
	v_add_f32_e32 v75, v22, v23
	s_waitcnt lgkmcnt(0)
	v_cndmask_b32_e64 v23, v19, v58, s[0:1]
	v_mov_b32_e32 v22, v81
	v_add_f32_e32 v82, v20, v21
	v_and_b32_e32 v119, 0xffff0000, v87
	v_fma_f32 v58, v22, v120, v82
	v_fma_f32 v58, v23, v121, v58
	ds_bpermute_b32 v59, v237, v58
	v_lshlrev_b32_e32 v118, 16, v87
	v_and_b32_e32 v87, 0xffff0000, v86
	v_lshlrev_b32_e32 v86, 16, v86
	v_add_f32_e32 v39, v84, v85
	v_add_f32_e32 v10, v99, v10
	v_fma_f32 v20, v80, v86, v39
	v_add_f32_e32 v39, v10, v11
	v_pk_mul_f32 v[10:11], v[80:81], v[56:57]
	v_fma_f32 v80, v81, v87, v20
	s_waitcnt lgkmcnt(0)
	v_cndmask_b32_e64 v21, v59, v58, s[0:1]
	v_mov_b32_e32 v20, v23
	ds_read_b64 v[92:93], v236 offset:57698
	v_fma_f32 v56, v20, v118, v80
	v_fma_f32 v59, v21, v119, v56
	v_add_f32_e32 v8, v8, v90
	ds_read_b96 v[88:90], v236 offset:57840
	ds_bpermute_b32 v56, v237, v59
	v_add_f32_e32 v10, v75, v10
	v_fma_f32 v22, v22, v122, v39
	s_waitcnt lgkmcnt(1)
	v_and_b32_e32 v117, 0xffff0000, v89
	v_lshlrev_b32_e32 v116, 16, v89
	v_and_b32_e32 v89, 0xffff0000, v88
	v_lshlrev_b32_e32 v88, 16, v88
	v_fma_f32 v39, v23, v123, v22
	s_waitcnt lgkmcnt(0)
	v_cndmask_b32_e64 v23, v56, v59, s[0:1]
	v_mov_b32_e32 v22, v21
	v_and_b32_e32 v107, 0xffff0000, v110
	v_fma_f32 v39, v22, v88, v39
	v_fma_f32 v39, v23, v89, v39
	ds_bpermute_b32 v56, v237, v39
	v_add_f32_e32 v57, v10, v11
	v_lshlrev_b32_e32 v106, 16, v110
	v_fma_f32 v10, v20, v14, v57
	v_fma_f32 v14, v21, v15, v10
	s_waitcnt lgkmcnt(0)
	v_cndmask_b32_e64 v11, v56, v39, s[0:1]
	v_mov_b32_e32 v10, v23
	v_and_b32_e32 v115, 0xffff0000, v111
	v_fma_f32 v12, v10, v12, v14
	v_fma_f32 v56, v11, v13, v12
	ds_bpermute_b32 v14, v237, v56
	v_lshlrev_b32_e32 v114, 16, v111
	v_fma_f32 v12, v22, v106, v58
	v_fma_f32 v20, v23, v107, v12
	s_waitcnt lgkmcnt(0)
	v_cndmask_b32_e64 v13, v14, v56, s[0:1]
	v_mov_b32_e32 v12, v11
	v_and_b32_e32 v113, 0xffff0000, v93
	v_fma_f32 v14, v12, v114, v20
	v_fma_f32 v20, v13, v115, v14
	ds_bpermute_b32 v14, v237, v20
	v_lshlrev_b32_e32 v112, 16, v93
	v_and_b32_e32 v93, 0xffff0000, v92
	v_lshlrev_b32_e32 v92, 16, v92
	s_waitcnt lgkmcnt(0)
	v_cndmask_b32_e64 v15, v20, v14, s[0:1]
	v_fma_f32 v10, v10, v92, v59
	v_mov_b32_e32 v14, v13
	v_fma_f32 v21, v11, v93, v10
	v_pk_mul_f32 v[10:11], v[12:13], v[116:117]
	v_add_f32_e32 v10, v39, v10
	v_fma_f32 v12, v14, v112, v21
	v_fma_f32 v21, v15, v113, v12
	ds_bpermute_b32 v12, v237, v21
	v_add_f32_e32 v22, v10, v11
	v_and_b32_e32 v11, 0xffff0000, v90
	v_lshlrev_b32_e32 v10, 16, v90
	v_add_f32_e32 v39, v8, v91
	s_waitcnt lgkmcnt(0)
	v_cndmask_b32_e64 v13, v21, v12, s[0:1]
	v_mov_b32_e32 v12, v15
	v_and_b32_e32 v57, 0xffff0000, v9
	v_fma_f32 v10, v12, v10, v22
	v_fma_f32 v22, v13, v11, v10
	ds_bpermute_b32 v12, v237, v22
	v_fma_f32 v8, v14, v60, v56
	v_fma_f32 v23, v15, v61, v8
	v_lshlrev_b32_e32 v56, 16, v9
	ds_read2_b64 v[8:11], v100 offset0:8 offset1:10
	s_waitcnt lgkmcnt(1)
	v_cndmask_b32_e64 v15, v22, v12, s[0:1]
	v_mov_b32_e32 v14, v13
	v_pk_mul_f32 v[12:13], v[14:15], v[56:57]
	ds_read2_b64 v[56:59], v98 offset0:136 offset1:138
	s_waitcnt lgkmcnt(1)
	v_cndmask_b32_e64 v11, v11, 0, s[4:5]
	v_cndmask_b32_e64 v10, v10, 0, s[4:5]
	v_cndmask_b32_e64 v9, v9, 0, s[4:5]
	v_cndmask_b32_e64 v8, v8, 0, s[4:5]
	v_add_f32_e32 v12, v23, v12
	v_add_f32_e32 v23, v12, v13
	v_cvt_pk_bf16_f32 v12, v32, v33
	v_cvt_pk_bf16_f32 v13, v34, v35
	v_cvt_pk_bf16_f32 v14, v36, v37
	v_cvt_pk_bf16_f32 v15, v38, v39
	v_add_u32_e32 v97, 0xc000, v236
	ds_read_b96 v[122:124], v236 offset:49792
	ds_read_b96 v[130:132], v236 offset:49936
	v_mfma_f32_32x32x16_bf16 v[32:47], v[8:11], v[12:15], v[32:47]
	s_waitcnt lgkmcnt(2)
	v_cndmask_b32_e64 v11, v59, 0, s[4:5]
	v_cndmask_b32_e64 v10, v58, 0, s[4:5]
	v_cndmask_b32_e64 v9, v57, 0, s[4:5]
	v_cndmask_b32_e64 v8, v56, 0, s[4:5]
	v_cvt_pk_bf16_f32 v12, v16, v17
	v_cvt_pk_bf16_f32 v13, v18, v19
	v_cvt_pk_bf16_f32 v14, v20, v21
	v_cvt_pk_bf16_f32 v15, v22, v23
	s_nop 2
	ds_bpermute_b32 v56, v237, v40
	ds_read_b96 v[126:128], v236 offset:59008
	v_mfma_f32_32x32x16_bf16 v[16:31], v[8:11], v[12:15], v[16:31]
	ds_read2_b64 v[8:11], v97 offset0:44 offset1:62
	v_add_u32_e32 v12, 0xe000, v236
	ds_read2_b64 v[12:15], v12 offset0:172 offset1:190
	s_waitcnt lgkmcnt(3)
	v_cndmask_b32_e64 v125, v56, v40, s[0:1]
	ds_read_b128 v[86:89], v236 offset:50656
	ds_read_b128 v[98:101], v236 offset:50800
	s_waitcnt lgkmcnt(3)
	v_lshlrev_b32_e32 v56, 16, v8
	s_nop 2
	ds_bpermute_b32 v57, v237, v24
	v_fma_f32 v85, v125, v56, v40
	s_waitcnt lgkmcnt(3)
	v_lshlrev_b32_e32 v40, 16, v12
	ds_read_b128 v[90:93], v236 offset:59872
	ds_read_b128 v[102:105], v236 offset:60016
	s_waitcnt lgkmcnt(2)
	v_cndmask_b32_e64 v129, v57, v24, s[0:1]
	v_fma_f32 v84, v129, v40, v24
	v_lshlrev_b32_e32 v24, 16, v10
	v_fma_f32 v83, v125, v24, v41
	v_lshlrev_b32_e32 v24, 16, v14
	v_fma_f32 v82, v129, v24, v25
	v_lshlrev_b32_e32 v24, 16, v122
	v_fma_f32 v81, v125, v24, v42
	ds_read_b96 v[40:42], v236 offset:59152
	v_lshlrev_b32_e32 v24, 16, v126
	v_fma_f32 v80, v129, v24, v26
	v_lshlrev_b32_e32 v24, 16, v130
	v_fma_f32 v75, v125, v24, v43
	s_waitcnt lgkmcnt(0)
	v_lshlrev_b32_e32 v24, 16, v40
	ds_read_b128 v[106:109], v236 offset:50944
	ds_read_b128 v[114:117], v236 offset:51088
	v_fma_f32 v61, v129, v24, v27
	v_lshlrev_b32_e32 v24, 16, v86
	ds_read_b128 v[110:113], v236 offset:60160
	ds_read_b128 v[118:121], v236 offset:60304
	v_fma_f32 v60, v125, v24, v44
	v_lshlrev_b32_e32 v24, 16, v90
	v_fma_f32 v59, v129, v24, v28
	v_lshlrev_b32_e32 v24, 16, v98
	v_fma_f32 v58, v125, v24, v45
	v_lshlrev_b32_e32 v24, 16, v102
	ds_bpermute_b32 v25, v237, v83
	v_fma_f32 v57, v129, v24, v29
	s_waitcnt lgkmcnt(4)
	v_lshlrev_b32_e32 v24, 16, v106
	ds_bpermute_b32 v26, v237, v82
	v_fma_f32 v56, v125, v24, v46
	s_waitcnt lgkmcnt(3)
	v_lshlrev_b32_e32 v24, 16, v110
	v_fma_f32 v43, v129, v24, v30
	v_lshlrev_b32_e32 v24, 16, v114
	v_fma_f32 v47, v125, v24, v47
	s_waitcnt lgkmcnt(2)
	v_lshlrev_b32_e32 v24, 16, v118
	v_fma_f32 v27, v129, v24, v31
	s_waitcnt lgkmcnt(1)
	v_cndmask_b32_e64 v24, v25, v83, s[0:1]
	v_and_b32_e32 v8, 0xffff0000, v8
	s_waitcnt lgkmcnt(0)
	v_cndmask_b32_e64 v25, v26, v82, s[0:1]
	v_fmac_f32_e32 v85, v24, v8
	v_and_b32_e32 v8, 0xffff0000, v12
	v_fmac_f32_e32 v84, v25, v8
	v_and_b32_e32 v8, 0xffff0000, v10
	v_fmac_f32_e32 v83, v24, v8
	v_and_b32_e32 v8, 0xffff0000, v14
	v_fmac_f32_e32 v82, v25, v8
	v_and_b32_e32 v8, 0xffff0000, v122
	v_fmac_f32_e32 v81, v24, v8
	v_and_b32_e32 v8, 0xffff0000, v126
	v_fmac_f32_e32 v80, v25, v8
	v_and_b32_e32 v8, 0xffff0000, v130
	v_fmac_f32_e32 v75, v24, v8
	v_and_b32_e32 v8, 0xffff0000, v40
	v_fmac_f32_e32 v61, v25, v8
	v_and_b32_e32 v8, 0xffff0000, v86
	v_fmac_f32_e32 v60, v24, v8
	v_and_b32_e32 v8, 0xffff0000, v90
	v_fmac_f32_e32 v59, v25, v8
	v_and_b32_e32 v8, 0xffff0000, v98
	v_fmac_f32_e32 v58, v24, v8
	v_and_b32_e32 v8, 0xffff0000, v102
	ds_bpermute_b32 v10, v237, v81
	ds_bpermute_b32 v12, v237, v80
	v_fmac_f32_e32 v57, v25, v8
	v_and_b32_e32 v8, 0xffff0000, v106
	v_fmac_f32_e32 v56, v24, v8
	v_and_b32_e32 v8, 0xffff0000, v110
	v_fmac_f32_e32 v43, v25, v8
	v_and_b32_e32 v8, 0xffff0000, v114
	v_fmac_f32_e32 v47, v24, v8
	v_and_b32_e32 v8, 0xffff0000, v118
	v_fmac_f32_e32 v27, v25, v8
	s_waitcnt lgkmcnt(1)
	v_cndmask_b32_e64 v8, v10, v81, s[0:1]
	s_waitcnt lgkmcnt(0)
	v_cndmask_b32_e64 v10, v12, v80, s[0:1]
	v_lshlrev_b32_e32 v12, 16, v9
	v_fmac_f32_e32 v85, v8, v12
	v_lshlrev_b32_e32 v12, 16, v13
	v_fmac_f32_e32 v84, v10, v12
	v_lshlrev_b32_e32 v12, 16, v11
	v_fmac_f32_e32 v83, v8, v12
	v_lshlrev_b32_e32 v12, 16, v15
	v_fmac_f32_e32 v82, v10, v12
	v_lshlrev_b32_e32 v12, 16, v123
	v_fmac_f32_e32 v81, v8, v12
	v_lshlrev_b32_e32 v12, 16, v127
	v_fmac_f32_e32 v80, v10, v12
	v_lshlrev_b32_e32 v12, 16, v131
	v_fmac_f32_e32 v75, v8, v12
	v_lshlrev_b32_e32 v12, 16, v41
	v_fmac_f32_e32 v61, v10, v12
	v_lshlrev_b32_e32 v12, 16, v87
	v_fmac_f32_e32 v60, v8, v12
	v_lshlrev_b32_e32 v12, 16, v91
	v_fmac_f32_e32 v59, v10, v12
	v_lshlrev_b32_e32 v12, 16, v99
	v_fmac_f32_e32 v58, v8, v12
	v_lshlrev_b32_e32 v12, 16, v103
	ds_bpermute_b32 v14, v237, v75
	v_fmac_f32_e32 v57, v10, v12
	v_lshlrev_b32_e32 v12, 16, v107
	ds_bpermute_b32 v24, v237, v61
	v_fmac_f32_e32 v56, v8, v12
	v_lshlrev_b32_e32 v12, 16, v111
	v_fmac_f32_e32 v43, v10, v12
	v_lshlrev_b32_e32 v12, 16, v115
	v_fmac_f32_e32 v47, v8, v12
	v_lshlrev_b32_e32 v8, 16, v119
	v_fmac_f32_e32 v27, v10, v8
	s_waitcnt lgkmcnt(1)
	v_cndmask_b32_e64 v8, v14, v75, s[0:1]
	v_and_b32_e32 v9, 0xffff0000, v9
	s_waitcnt lgkmcnt(0)
	v_cndmask_b32_e64 v10, v24, v61, s[0:1]
	v_fmac_f32_e32 v85, v8, v9
	v_and_b32_e32 v9, 0xffff0000, v13
	v_fmac_f32_e32 v84, v10, v9
	v_and_b32_e32 v9, 0xffff0000, v11
	v_fmac_f32_e32 v83, v8, v9
	v_and_b32_e32 v9, 0xffff0000, v15
	v_fmac_f32_e32 v82, v10, v9
	v_and_b32_e32 v9, 0xffff0000, v123
	v_fmac_f32_e32 v81, v8, v9
	v_and_b32_e32 v9, 0xffff0000, v127
	v_fmac_f32_e32 v80, v10, v9
	v_and_b32_e32 v9, 0xffff0000, v131
	v_fmac_f32_e32 v75, v8, v9
	v_and_b32_e32 v9, 0xffff0000, v41
	v_fmac_f32_e32 v61, v10, v9
	v_and_b32_e32 v9, 0xffff0000, v87
	v_fmac_f32_e32 v60, v8, v9
	v_and_b32_e32 v9, 0xffff0000, v91
	v_fmac_f32_e32 v59, v10, v9
	v_and_b32_e32 v9, 0xffff0000, v99
	v_fmac_f32_e32 v58, v8, v9
	v_and_b32_e32 v9, 0xffff0000, v103
	v_fmac_f32_e32 v57, v10, v9
	v_and_b32_e32 v9, 0xffff0000, v107
	v_fmac_f32_e32 v56, v8, v9
	v_and_b32_e32 v9, 0xffff0000, v111
	v_fmac_f32_e32 v43, v10, v9
	v_and_b32_e32 v9, 0xffff0000, v115
	v_fmac_f32_e32 v47, v8, v9
	v_and_b32_e32 v8, 0xffff0000, v119
	ds_bpermute_b32 v11, v237, v84
	v_fmac_f32_e32 v27, v10, v8
	ds_read_u16 v8, v236 offset:58872
	ds_read_u16 v12, v236 offset:49656
	ds_read_b96 v[44:46], v236 offset:51104
	ds_bpermute_b32 v9, v237, v85
	s_waitcnt lgkmcnt(4)
	v_cndmask_b32_e64 v10, v84, v11, s[0:1]
	s_waitcnt lgkmcnt(3)
	v_lshlrev_b32_e32 v8, 16, v8
	v_fmac_f32_e32 v82, v10, v8
	v_lshlrev_b32_e32 v8, 16, v124
	s_waitcnt lgkmcnt(0)
	v_cndmask_b32_e64 v9, v85, v9, s[0:1]
	v_fmac_f32_e32 v81, v9, v8
	v_lshlrev_b32_e32 v8, 16, v128
	v_fmac_f32_e32 v80, v10, v8
	v_lshlrev_b32_e32 v8, 16, v132
	v_fmac_f32_e32 v75, v9, v8
	v_lshlrev_b32_e32 v8, 16, v42
	v_fmac_f32_e32 v61, v10, v8
	v_lshlrev_b32_e32 v8, 16, v88
	v_lshlrev_b32_e32 v11, 16, v12
	v_fmac_f32_e32 v60, v9, v8
	v_lshlrev_b32_e32 v8, 16, v92
	v_fmac_f32_e32 v83, v9, v11
	v_fmac_f32_e32 v59, v10, v8
	v_lshlrev_b32_e32 v8, 16, v100
	v_fmac_f32_e32 v58, v9, v8
	v_lshlrev_b32_e32 v8, 16, v104
	ds_bpermute_b32 v11, v237, v83
	v_fmac_f32_e32 v57, v10, v8
	v_lshlrev_b32_e32 v8, 16, v108
	ds_bpermute_b32 v12, v237, v82
	v_fmac_f32_e32 v56, v9, v8
	v_lshlrev_b32_e32 v8, 16, v112
	v_fmac_f32_e32 v43, v10, v8
	v_lshlrev_b32_e32 v8, 16, v116
	v_fmac_f32_e32 v47, v9, v8
	v_lshlrev_b32_e32 v8, 16, v120
	v_fmac_f32_e32 v27, v10, v8
	s_waitcnt lgkmcnt(1)
	v_cndmask_b32_e64 v8, v83, v11, s[0:1]
	v_and_b32_e32 v10, 0xffff0000, v124
	s_waitcnt lgkmcnt(0)
	v_cndmask_b32_e64 v9, v82, v12, s[0:1]
	v_fmac_f32_e32 v81, v8, v10
	v_and_b32_e32 v10, 0xffff0000, v128
	v_fmac_f32_e32 v80, v9, v10
	v_and_b32_e32 v10, 0xffff0000, v132
	v_fmac_f32_e32 v75, v8, v10
	v_and_b32_e32 v10, 0xffff0000, v42
	v_fmac_f32_e32 v61, v9, v10
	v_and_b32_e32 v10, 0xffff0000, v88
	v_fmac_f32_e32 v60, v8, v10
	v_and_b32_e32 v10, 0xffff0000, v92
	v_fmac_f32_e32 v59, v9, v10
	v_and_b32_e32 v10, 0xffff0000, v100
	v_fmac_f32_e32 v58, v8, v10
	v_and_b32_e32 v10, 0xffff0000, v104
	v_fmac_f32_e32 v57, v9, v10
	v_and_b32_e32 v10, 0xffff0000, v108
	v_fmac_f32_e32 v56, v8, v10
	v_and_b32_e32 v10, 0xffff0000, v112
	v_fmac_f32_e32 v43, v9, v10
	v_and_b32_e32 v10, 0xffff0000, v116
	v_fmac_f32_e32 v47, v8, v10
	v_and_b32_e32 v8, 0xffff0000, v120
	ds_bpermute_b32 v10, v237, v81
	ds_bpermute_b32 v11, v237, v80
	ds_read_u16 v12, v236 offset:49948
	v_fmac_f32_e32 v27, v9, v8
	ds_read_u16 v8, v236 offset:59164
	s_waitcnt lgkmcnt(3)
	v_cndmask_b32_e64 v9, v81, v10, s[0:1]
	s_waitcnt lgkmcnt(2)
	v_cndmask_b32_e64 v10, v80, v11, s[0:1]
	s_waitcnt lgkmcnt(1)
	v_lshlrev_b32_e32 v11, 16, v12
	v_fmac_f32_e32 v75, v9, v11
	s_waitcnt lgkmcnt(0)
	v_lshlrev_b32_e32 v8, 16, v8
	v_fmac_f32_e32 v61, v10, v8
	v_lshlrev_b32_e32 v8, 16, v89
	v_fmac_f32_e32 v60, v9, v8
	v_lshlrev_b32_e32 v8, 16, v93
	v_fmac_f32_e32 v59, v10, v8
	v_lshlrev_b32_e32 v8, 16, v101
	v_fmac_f32_e32 v58, v9, v8
	v_lshlrev_b32_e32 v8, 16, v105
	ds_bpermute_b32 v11, v237, v75
	v_fmac_f32_e32 v57, v10, v8
	v_lshlrev_b32_e32 v8, 16, v109
	ds_bpermute_b32 v12, v237, v61
	v_fmac_f32_e32 v56, v9, v8
	v_lshlrev_b32_e32 v8, 16, v113
	v_fmac_f32_e32 v43, v10, v8
	v_lshlrev_b32_e32 v8, 16, v117
	v_fmac_f32_e32 v47, v9, v8
	v_lshlrev_b32_e32 v8, 16, v121
	v_fmac_f32_e32 v27, v10, v8
	s_waitcnt lgkmcnt(1)
	v_cndmask_b32_e64 v8, v75, v11, s[0:1]
	v_and_b32_e32 v10, 0xffff0000, v89
	s_waitcnt lgkmcnt(0)
	v_cndmask_b32_e64 v9, v61, v12, s[0:1]
	v_fmac_f32_e32 v60, v8, v10
	v_and_b32_e32 v10, 0xffff0000, v93
	v_fmac_f32_e32 v59, v9, v10
	v_and_b32_e32 v10, 0xffff0000, v101
	v_fmac_f32_e32 v58, v8, v10
	v_and_b32_e32 v10, 0xffff0000, v105
	v_fmac_f32_e32 v57, v9, v10
	v_and_b32_e32 v10, 0xffff0000, v109
	v_fmac_f32_e32 v56, v8, v10
	v_and_b32_e32 v10, 0xffff0000, v113
	v_fmac_f32_e32 v43, v9, v10
	v_and_b32_e32 v10, 0xffff0000, v117
	v_fmac_f32_e32 v47, v8, v10
	v_and_b32_e32 v8, 0xffff0000, v121
	v_fmac_f32_e32 v27, v9, v8
	ds_bpermute_b32 v24, v237, v60
	ds_read2_b64 v[8:11], v97 offset0:190 offset1:208
	v_add_u32_e32 v12, 0xe800, v236
	ds_bpermute_b32 v25, v237, v59
	ds_read2_b64 v[12:15], v12 offset0:62 offset1:80
	s_waitcnt lgkmcnt(3)
	v_cndmask_b32_e64 v86, v24, v60, s[0:1]
	s_waitcnt lgkmcnt(2)
	v_lshlrev_b32_e32 v24, 16, v8
	v_fmac_f32_e32 v60, v86, v24
	s_waitcnt lgkmcnt(1)
	v_cndmask_b32_e64 v31, v25, v59, s[0:1]
	s_waitcnt lgkmcnt(0)
	v_lshlrev_b32_e32 v24, 16, v12
	v_fmac_f32_e32 v59, v31, v24
	v_lshlrev_b32_e32 v28, 16, v10
	ds_read_b96 v[24:26], v236 offset:50960
	v_fmac_f32_e32 v58, v86, v28
	ds_read_b96 v[28:30], v236 offset:60176
	v_lshlrev_b32_e32 v40, 16, v14
	v_fmac_f32_e32 v57, v31, v40
	s_waitcnt lgkmcnt(1)
	v_lshlrev_b32_e32 v40, 16, v24
	v_fmac_f32_e32 v56, v86, v40
	s_waitcnt lgkmcnt(0)
	v_lshlrev_b32_e32 v40, 16, v28
	v_fmac_f32_e32 v43, v31, v40
	ds_read_b96 v[40:42], v236 offset:60320
	ds_bpermute_b32 v88, v237, v58
	ds_bpermute_b32 v89, v237, v57
	v_lshlrev_b32_e32 v87, 16, v44
	v_fmac_f32_e32 v47, v86, v87
	s_waitcnt lgkmcnt(2)
	v_lshlrev_b32_e32 v86, 16, v40
	v_fmac_f32_e32 v27, v31, v86
	s_waitcnt lgkmcnt(1)
	v_cndmask_b32_e64 v31, v88, v58, s[0:1]
	v_and_b32_e32 v8, 0xffff0000, v8
	s_waitcnt lgkmcnt(0)
	v_cndmask_b32_e64 v86, v89, v57, s[0:1]
	v_fmac_f32_e32 v60, v31, v8
	v_and_b32_e32 v8, 0xffff0000, v12
	v_fmac_f32_e32 v59, v86, v8
	v_and_b32_e32 v8, 0xffff0000, v10
	v_fmac_f32_e32 v58, v31, v8
	v_and_b32_e32 v8, 0xffff0000, v14
	v_fmac_f32_e32 v57, v86, v8
	v_and_b32_e32 v8, 0xffff0000, v24
	v_fmac_f32_e32 v56, v31, v8
	v_and_b32_e32 v8, 0xffff0000, v28
	v_fmac_f32_e32 v43, v86, v8
	ds_bpermute_b32 v10, v237, v56
	ds_bpermute_b32 v12, v237, v43
	v_and_b32_e32 v8, 0xffff0000, v44
	v_fmac_f32_e32 v47, v31, v8
	v_and_b32_e32 v8, 0xffff0000, v40
	v_fmac_f32_e32 v27, v86, v8
	s_waitcnt lgkmcnt(1)
	v_cndmask_b32_e64 v8, v10, v56, s[0:1]
	v_lshlrev_b32_e32 v14, 16, v45
	s_waitcnt lgkmcnt(0)
	v_cndmask_b32_e64 v10, v12, v43, s[0:1]
	v_lshlrev_b32_e32 v12, 16, v9
	v_fmac_f32_e32 v47, v8, v14
	v_lshlrev_b32_e32 v14, 16, v41
	v_fmac_f32_e32 v60, v8, v12
	v_lshlrev_b32_e32 v12, 16, v13
	v_fmac_f32_e32 v27, v10, v14
	ds_bpermute_b32 v14, v237, v47
	v_fmac_f32_e32 v59, v10, v12
	v_lshlrev_b32_e32 v12, 16, v11
	ds_bpermute_b32 v24, v237, v27
	v_fmac_f32_e32 v58, v8, v12
	v_lshlrev_b32_e32 v12, 16, v15
	v_fmac_f32_e32 v57, v10, v12
	v_lshlrev_b32_e32 v12, 16, v25
	v_fmac_f32_e32 v56, v8, v12
	v_lshlrev_b32_e32 v8, 16, v29
	v_fmac_f32_e32 v43, v10, v8
	s_waitcnt lgkmcnt(1)
	v_cndmask_b32_e64 v8, v14, v47, s[0:1]
	v_and_b32_e32 v9, 0xffff0000, v9
	s_waitcnt lgkmcnt(0)
	v_cndmask_b32_e64 v14, v24, v27, s[0:1]
	v_fmac_f32_e32 v60, v8, v9
	v_and_b32_e32 v9, 0xffff0000, v13
	v_fmac_f32_e32 v59, v14, v9
	v_and_b32_e32 v9, 0xffff0000, v11
	v_fmac_f32_e32 v58, v8, v9
	v_and_b32_e32 v9, 0xffff0000, v15
	v_fmac_f32_e32 v57, v14, v9
	v_and_b32_e32 v9, 0xffff0000, v25
	v_fmac_f32_e32 v56, v8, v9
	v_and_b32_e32 v9, 0xffff0000, v29
	v_fmac_f32_e32 v43, v14, v9
	v_and_b32_e32 v9, 0xffff0000, v45
	ds_bpermute_b32 v10, v237, v60
	ds_read_u16 v12, v236 offset:50824
	ds_bpermute_b32 v11, v237, v59
	v_fmac_f32_e32 v47, v8, v9
	ds_read_u16 v8, v236 offset:60040
	s_waitcnt lgkmcnt(3)
	v_cndmask_b32_e64 v9, v60, v10, s[0:1]
	s_waitcnt lgkmcnt(2)
	v_lshlrev_b32_e32 v10, 16, v12
	s_waitcnt lgkmcnt(1)
	v_cndmask_b32_e64 v15, v59, v11, s[0:1]
	v_fmac_f32_e32 v58, v9, v10
	s_waitcnt lgkmcnt(0)
	v_lshlrev_b32_e32 v8, 16, v8
	v_fmac_f32_e32 v57, v15, v8
	ds_bpermute_b32 v10, v237, v58
	ds_bpermute_b32 v11, v237, v57
	v_lshlrev_b32_e32 v8, 16, v26
	v_fmac_f32_e32 v56, v9, v8
	v_lshlrev_b32_e32 v8, 16, v30
	v_fmac_f32_e32 v43, v15, v8
	v_lshlrev_b32_e32 v8, 16, v46
	v_fmac_f32_e32 v47, v9, v8
	s_waitcnt lgkmcnt(1)
	v_cndmask_b32_e64 v8, v58, v10, s[0:1]
	v_and_b32_e32 v9, 0xffff0000, v26
	s_waitcnt lgkmcnt(0)
	v_cndmask_b32_e64 v24, v57, v11, s[0:1]
	v_fmac_f32_e32 v56, v8, v9
	v_and_b32_e32 v9, 0xffff0000, v30
	v_fmac_f32_e32 v43, v24, v9
	ds_bpermute_b32 v9, v237, v56
	ds_read_u16 v10, v236 offset:51116
	ds_read_u16 v28, v236 offset:60332
	v_and_b32_e32 v11, 0xffff0000, v46
	v_fmac_f32_e32 v47, v8, v11
	s_waitcnt lgkmcnt(2)
	v_cndmask_b32_e64 v8, v56, v9, s[0:1]
	s_waitcnt lgkmcnt(1)
	v_lshlrev_b32_e32 v9, 16, v10
	v_fmac_f32_e32 v47, v8, v9
	v_or3_b32 v8, s2, v176, v154
	v_mov_b32_e32 v9, s3
	v_lshl_add_u64 v[10:11], v[78:79], 0, v[76:77]
	v_lshl_add_u64 v[10:11], v[8:9], 1, v[10:11]
	v_cndmask_b32_e64 v12, -v48, v48, vcc
	v_mul_u32_u24_e32 v176, 0xc00, v185
	v_lshl_add_u64 v[8:9], v[10:11], 0, s[86:87]
	v_cvt_pk_bf16_f32 v26, v12, s0
	v_lshl_add_u64 v[12:13], v[10:11], 0, v[176:177]
	v_mul_u32_u24_e32 v176, 0x300, v157
	global_store_short v[12:13], v26, off
	v_cvt_pk_bf16_f32 v0, v0, s0
	v_lshl_add_u64 v[12:13], v[8:9], 0, v[176:177]
	global_store_short v[12:13], v0, off
	v_cndmask_b32_e64 v0, -v49, v49, vcc
	v_mul_u32_u24_e32 v176, 0x300, v156
	v_cvt_pk_bf16_f32 v0, v0, s0
	v_lshl_add_u64 v[12:13], v[10:11], 0, v[176:177]
	global_store_short v[12:13], v0, off
	v_cndmask_b32_e64 v0, -v1, v1, vcc
	v_cvt_pk_bf16_f32 v26, v0, s0
	v_mul_u32_u24_e32 v0, 0x300, v158
	v_mov_b32_e32 v1, v177
	v_lshl_add_u64 v[0:1], v[8:9], 0, v[0:1]
	global_store_short v[0:1], v26, off
	v_cndmask_b32_e64 v0, -v50, v50, vcc
	v_cvt_pk_bf16_f32 v0, v0, s0
	global_store_short v[12:13], v0, off offset:768
	v_cndmask_b32_e64 v0, -v2, v2, vcc
	v_cvt_pk_bf16_f32 v2, v0, s0
	v_mul_u32_u24_e32 v0, 0x300, v159
	v_mov_b32_e32 v1, v177
	v_lshl_add_u64 v[0:1], v[8:9], 0, v[0:1]
	global_store_short v[0:1], v2, off
	v_cndmask_b32_e64 v0, -v51, v51, vcc
	v_cvt_pk_bf16_f32 v2, v0, s0
	v_mov_b32_e32 v0, 0x600
	v_mad_u32_u24 v0, v156, s89, v0
	v_mov_b32_e32 v1, v177
	v_lshl_add_u64 v[0:1], v[10:11], 0, v[0:1]
	global_store_short v[0:1], v2, off
	v_cndmask_b32_e64 v0, -v3, v3, vcc
	v_cvt_pk_bf16_f32 v2, v0, s0
	v_mul_u32_u24_e32 v0, 0x300, v160
	v_mov_b32_e32 v1, v177
	v_lshl_add_u64 v[0:1], v[8:9], 0, v[0:1]
	global_store_short v[0:1], v2, off
	v_cndmask_b32_e64 v0, -v52, v52, vcc
	v_cvt_pk_bf16_f32 v2, v0, s0
	v_mov_b32_e32 v0, 0x1500
	v_mad_u32_u24 v0, v156, s89, v0
	v_mov_b32_e32 v1, v177
	v_lshl_add_u64 v[0:1], v[10:11], 0, v[0:1]
	global_store_short v[0:1], v2, off
	v_cndmask_b32_e64 v0, -v4, v4, vcc
	v_cvt_pk_bf16_f32 v2, v0, s0
	v_mul_u32_u24_e32 v0, 0x300, v161
	v_mov_b32_e32 v1, v177
	v_lshl_add_u64 v[0:1], v[8:9], 0, v[0:1]
	global_store_short v[0:1], v2, off
	v_cndmask_b32_e64 v0, -v53, v53, vcc
	v_cvt_pk_bf16_f32 v2, v0, s0
	v_mad_u32_u24 v0, v156, s89, v252
	v_mov_b32_e32 v1, v177
	v_lshl_add_u64 v[0:1], v[10:11], 0, v[0:1]
	global_store_short v[0:1], v2, off
	v_cndmask_b32_e64 v0, -v5, v5, vcc
	v_cvt_pk_bf16_f32 v2, v0, s0
	v_mul_u32_u24_e32 v0, 0x300, v162
	v_mov_b32_e32 v1, v177
	v_lshl_add_u64 v[0:1], v[8:9], 0, v[0:1]
	global_store_short v[0:1], v2, off
	v_cndmask_b32_e64 v0, -v54, v54, vcc
	v_cvt_pk_bf16_f32 v2, v0, s0
	v_mad_u32_u24 v0, v156, s89, v230
	v_mov_b32_e32 v1, v177
	v_lshl_add_u64 v[0:1], v[10:11], 0, v[0:1]
	global_store_short v[0:1], v2, off
	v_cndmask_b32_e64 v0, -v6, v6, vcc
	v_cvt_pk_bf16_f32 v2, v0, s0
	v_mul_u32_u24_e32 v0, 0x300, v163
	v_mov_b32_e32 v1, v177
	v_lshl_add_u64 v[0:1], v[8:9], 0, v[0:1]
	global_store_short v[0:1], v2, off
	v_cndmask_b32_e64 v0, -v55, v55, vcc
	v_cvt_pk_bf16_f32 v2, v0, s0
	v_mad_u32_u24 v0, v156, s89, v191
	v_mov_b32_e32 v1, v177
	v_lshl_add_u64 v[0:1], v[10:11], 0, v[0:1]
	global_store_short v[0:1], v2, off
	v_cndmask_b32_e64 v0, -v7, v7, vcc
	v_cvt_pk_bf16_f32 v2, v0, s0
	v_mul_u32_u24_e32 v0, 0x300, v164
	v_mov_b32_e32 v1, v177
	v_lshl_add_u64 v[0:1], v[8:9], 0, v[0:1]
	global_store_short v[0:1], v2, off
	v_cndmask_b32_e64 v0, -v63, v63, vcc
	v_cvt_pk_bf16_f32 v2, v0, s0
	v_mad_u32_u24 v0, v156, s89, v190
	v_mov_b32_e32 v1, v177
	v_lshl_add_u64 v[0:1], v[10:11], 0, v[0:1]
	global_store_short v[0:1], v2, off
	v_cndmask_b32_e64 v0, -v69, v69, vcc
	v_cvt_pk_bf16_f32 v2, v0, s0
	v_mul_u32_u24_e32 v0, 0x300, v165
	v_mov_b32_e32 v1, v177
	v_lshl_add_u64 v[0:1], v[8:9], 0, v[0:1]
	global_store_short v[0:1], v2, off
	v_cndmask_b32_e64 v0, -v72, v72, vcc
	v_cvt_pk_bf16_f32 v2, v0, s0
	v_mad_u32_u24 v0, v156, s89, v208
	v_mov_b32_e32 v1, v177
	v_lshl_add_u64 v[0:1], v[10:11], 0, v[0:1]
	global_store_short v[0:1], v2, off
	v_cndmask_b32_e64 v0, -v70, v70, vcc
	v_cvt_pk_bf16_f32 v2, v0, s0
	v_mul_u32_u24_e32 v0, 0x300, v166
	v_mov_b32_e32 v1, v177
	v_lshl_add_u64 v[0:1], v[8:9], 0, v[0:1]
	global_store_short v[0:1], v2, off
	v_cndmask_b32_e64 v0, -v68, v68, vcc
	v_cvt_pk_bf16_f32 v2, v0, s0
	v_mad_u32_u24 v0, v156, s89, v209
	v_mov_b32_e32 v1, v177
	v_lshl_add_u64 v[0:1], v[10:11], 0, v[0:1]
	global_store_short v[0:1], v2, off
	v_cndmask_b32_e64 v0, -v67, v67, vcc
	v_cvt_pk_bf16_f32 v2, v0, s0
	v_mul_u32_u24_e32 v0, 0x300, v167
	v_mov_b32_e32 v1, v177
	v_lshl_add_u64 v[0:1], v[8:9], 0, v[0:1]
	global_store_short v[0:1], v2, off
	v_cndmask_b32_e64 v0, -v62, v62, vcc
	v_cvt_pk_bf16_f32 v2, v0, s0
	v_mad_u32_u24 v0, v156, s89, v210
	v_mov_b32_e32 v1, v177
	v_lshl_add_u64 v[0:1], v[10:11], 0, v[0:1]
	global_store_short v[0:1], v2, off
	v_cndmask_b32_e64 v0, -v66, v66, vcc
	v_cvt_pk_bf16_f32 v2, v0, s0
	v_mul_u32_u24_e32 v0, 0x300, v168
	v_mov_b32_e32 v1, v177
	v_lshl_add_u64 v[0:1], v[8:9], 0, v[0:1]
	global_store_short v[0:1], v2, off
	v_cndmask_b32_e64 v0, -v96, v96, vcc
	v_cvt_pk_bf16_f32 v2, v0, s0
	v_mad_u32_u24 v0, v156, s89, v211
	v_mov_b32_e32 v1, v177
	v_lshl_add_u64 v[0:1], v[10:11], 0, v[0:1]
	global_store_short v[0:1], v2, off
	v_cndmask_b32_e64 v0, -v74, v74, vcc
	v_cvt_pk_bf16_f32 v2, v0, s0
	v_mul_u32_u24_e32 v0, 0x300, v169
	v_mov_b32_e32 v1, v177
	v_lshl_add_u64 v[0:1], v[8:9], 0, v[0:1]
	global_store_short v[0:1], v2, off
	v_cndmask_b32_e64 v0, -v95, v95, vcc
	v_cvt_pk_bf16_f32 v2, v0, s0
	v_mad_u32_u24 v0, v156, s89, v212
	v_mov_b32_e32 v1, v177
	v_lshl_add_u64 v[0:1], v[10:11], 0, v[0:1]
	global_store_short v[0:1], v2, off
	v_cndmask_b32_e64 v0, -v71, v71, vcc
	v_cvt_pk_bf16_f32 v2, v0, s0
	v_mul_u32_u24_e32 v0, 0x300, v170
	v_mov_b32_e32 v1, v177
	v_lshl_add_u64 v[0:1], v[8:9], 0, v[0:1]
	global_store_short v[0:1], v2, off
	v_cndmask_b32_e64 v0, -v94, v94, vcc
	v_cvt_pk_bf16_f32 v2, v0, s0
	v_mad_u32_u24 v0, v156, s89, v213
	v_mov_b32_e32 v1, v177
	v_lshl_add_u64 v[0:1], v[10:11], 0, v[0:1]
	global_store_short v[0:1], v2, off
	v_cndmask_b32_e64 v0, -v65, v65, vcc
	v_cvt_pk_bf16_f32 v2, v0, s0
	v_mul_u32_u24_e32 v0, 0x300, v171
	v_mov_b32_e32 v1, v177
	v_lshl_add_u64 v[0:1], v[8:9], 0, v[0:1]
	global_store_short v[0:1], v2, off
	v_cndmask_b32_e64 v0, -v64, v64, vcc
	v_cvt_pk_bf16_f32 v2, v0, s0
	v_mad_u32_u24 v0, v156, s89, v214
	v_mov_b32_e32 v1, v177
	v_lshl_add_u64 v[0:1], v[10:11], 0, v[0:1]
	global_store_short v[0:1], v2, off
	v_cndmask_b32_e64 v0, -v73, v73, vcc
	v_cvt_pk_bf16_f32 v2, v0, s0
	v_mul_u32_u24_e32 v0, 0x300, v172
	v_mov_b32_e32 v1, v177
	v_lshl_add_u64 v[0:1], v[8:9], 0, v[0:1]
	global_store_short v[0:1], v2, off
	v_cndmask_b32_e64 v0, -v32, v32, vcc
	v_cvt_pk_bf16_f32 v2, v0, s0
	v_mad_u32_u24 v0, v156, s89, v215
	v_mov_b32_e32 v1, v177
	v_lshl_add_u64 v[0:1], v[10:11], 0, v[0:1]
	global_store_short v[0:1], v2, off
	v_cndmask_b32_e64 v0, -v16, v16, vcc
	v_cvt_pk_bf16_f32 v2, v0, s0
	v_mul_u32_u24_e32 v0, 0x300, v173
	v_mov_b32_e32 v1, v177
	v_lshl_add_u64 v[0:1], v[8:9], 0, v[0:1]
	global_store_short v[0:1], v2, off
	v_cndmask_b32_e64 v0, -v33, v33, vcc
	v_or_b32_e32 v176, 0x6000, v176
	v_cvt_pk_bf16_f32 v2, v0, s0
	v_lshl_add_u64 v[0:1], v[10:11], 0, v[176:177]
	global_store_short v[0:1], v2, off
	v_cndmask_b32_e64 v0, -v17, v17, vcc
	v_mul_u32_u24_e32 v176, 0x300, v174
	v_cvt_pk_bf16_f32 v2, v0, s0
	v_lshl_add_u64 v[0:1], v[8:9], 0, v[176:177]
	global_store_short v[0:1], v2, off
	v_cndmask_b32_e64 v0, -v34, v34, vcc
	v_mad_u32_u24 v176, v156, s89, v216
	v_cvt_pk_bf16_f32 v2, v0, s0
	v_lshl_add_u64 v[0:1], v[10:11], 0, v[176:177]
	global_store_short v[0:1], v2, off
	v_cndmask_b32_e64 v0, -v18, v18, vcc
	v_mul_u32_u24_e32 v176, 0x300, v175
	v_cvt_pk_bf16_f32 v2, v0, s0
	v_lshl_add_u64 v[0:1], v[8:9], 0, v[176:177]
	global_store_short v[0:1], v2, off
	v_cndmask_b32_e64 v0, -v35, v35, vcc
	v_mad_u32_u24 v176, v156, s89, v217
	v_cvt_pk_bf16_f32 v2, v0, s0
	v_lshl_add_u64 v[0:1], v[10:11], 0, v[176:177]
	global_store_short v[0:1], v2, off
	v_cndmask_b32_e64 v0, -v19, v19, vcc
	v_mul_u32_u24_e32 v176, 0x300, v181
	v_cvt_pk_bf16_f32 v2, v0, s0
	v_lshl_add_u64 v[0:1], v[8:9], 0, v[176:177]
	global_store_short v[0:1], v2, off
	v_cndmask_b32_e64 v0, -v36, v36, vcc
	v_mad_u32_u24 v176, v156, s89, v218
	v_cvt_pk_bf16_f32 v2, v0, s0
	v_lshl_add_u64 v[0:1], v[10:11], 0, v[176:177]
	global_store_short v[0:1], v2, off
	v_cndmask_b32_e64 v0, -v20, v20, vcc
	v_mul_u32_u24_e32 v176, 0x300, v183
	v_cvt_pk_bf16_f32 v2, v0, s0
	v_lshl_add_u64 v[0:1], v[8:9], 0, v[176:177]
	global_store_short v[0:1], v2, off
	v_cndmask_b32_e64 v0, -v37, v37, vcc
	v_mad_u32_u24 v176, v156, s89, v219
	v_cvt_pk_bf16_f32 v2, v0, s0
	v_lshl_add_u64 v[0:1], v[10:11], 0, v[176:177]
	global_store_short v[0:1], v2, off
	v_cndmask_b32_e64 v0, -v21, v21, vcc
	v_mul_u32_u24_e32 v176, 0x300, v184
	v_cvt_pk_bf16_f32 v2, v0, s0
	v_lshl_add_u64 v[0:1], v[8:9], 0, v[176:177]
	global_store_short v[0:1], v2, off
	v_cndmask_b32_e64 v0, -v38, v38, vcc
	v_mad_u32_u24 v176, v156, s89, v220
	v_cvt_pk_bf16_f32 v2, v0, s0
	v_lshl_add_u64 v[0:1], v[10:11], 0, v[176:177]
	global_store_short v[0:1], v2, off
	v_cndmask_b32_e64 v0, -v22, v22, vcc
	v_mul_u32_u24_e32 v176, 0x300, v186
	v_cvt_pk_bf16_f32 v2, v0, s0
	v_lshl_add_u64 v[0:1], v[8:9], 0, v[176:177]
	global_store_short v[0:1], v2, off
	v_cndmask_b32_e64 v0, -v39, v39, vcc
	v_mad_u32_u24 v176, v156, s89, v221
	v_cvt_pk_bf16_f32 v2, v0, s0
	v_lshl_add_u64 v[0:1], v[10:11], 0, v[176:177]
	global_store_short v[0:1], v2, off
	v_cndmask_b32_e64 v0, -v23, v23, vcc
	v_mul_u32_u24_e32 v176, 0x300, v187
	v_cvt_pk_bf16_f32 v2, v0, s0
	v_lshl_add_u64 v[0:1], v[8:9], 0, v[176:177]
	global_store_short v[0:1], v2, off
	v_cndmask_b32_e64 v0, -v85, v85, vcc
	v_mad_u32_u24 v176, v156, s89, v222
	v_cvt_pk_bf16_f32 v2, v0, s0
	v_lshl_add_u64 v[0:1], v[10:11], 0, v[176:177]
	global_store_short v[0:1], v2, off
	v_cndmask_b32_e64 v0, -v84, v84, vcc
	v_mul_u32_u24_e32 v176, 0x300, v188
	v_cvt_pk_bf16_f32 v2, v0, s0
	v_lshl_add_u64 v[0:1], v[8:9], 0, v[176:177]
	global_store_short v[0:1], v2, off
	v_cndmask_b32_e64 v0, -v83, v83, vcc
	v_mad_u32_u24 v176, v156, s89, v223
	v_cvt_pk_bf16_f32 v2, v0, s0
	v_lshl_add_u64 v[0:1], v[10:11], 0, v[176:177]
	global_store_short v[0:1], v2, off
	v_cndmask_b32_e64 v0, -v82, v82, vcc
	v_mul_u32_u24_e32 v176, 0x300, v189
	v_cvt_pk_bf16_f32 v2, v0, s0
	v_lshl_add_u64 v[0:1], v[8:9], 0, v[176:177]
	global_store_short v[0:1], v2, off
	v_cndmask_b32_e64 v0, -v81, v81, vcc
	v_mad_u32_u24 v176, v156, s89, v224
	v_cvt_pk_bf16_f32 v2, v0, s0
	v_lshl_add_u64 v[0:1], v[10:11], 0, v[176:177]
	global_store_short v[0:1], v2, off
	v_cndmask_b32_e64 v0, -v80, v80, vcc
	v_mul_u32_u24_e32 v176, 0x300, v231
	v_cvt_pk_bf16_f32 v2, v0, s0
	v_lshl_add_u64 v[0:1], v[8:9], 0, v[176:177]
	global_store_short v[0:1], v2, off
	v_cndmask_b32_e64 v0, -v75, v75, vcc
	v_mad_u32_u24 v176, v156, s89, v225
	v_cvt_pk_bf16_f32 v2, v0, s0
	v_lshl_add_u64 v[0:1], v[10:11], 0, v[176:177]
	global_store_short v[0:1], v2, off
	v_cndmask_b32_e64 v0, -v61, v61, vcc
	v_mul_u32_u24_e32 v176, 0x300, v232
	v_cvt_pk_bf16_f32 v2, v0, s0
	v_lshl_add_u64 v[0:1], v[8:9], 0, v[176:177]
	global_store_short v[0:1], v2, off
	v_cndmask_b32_e64 v0, -v60, v60, vcc
	v_mad_u32_u24 v176, v156, s89, v226
	v_cvt_pk_bf16_f32 v2, v0, s0
	v_lshl_add_u64 v[0:1], v[10:11], 0, v[176:177]
	global_store_short v[0:1], v2, off
	v_cndmask_b32_e64 v0, -v59, v59, vcc
	v_mul_u32_u24_e32 v176, 0x300, v233
	v_cvt_pk_bf16_f32 v2, v0, s0
	v_lshl_add_u64 v[0:1], v[8:9], 0, v[176:177]
	global_store_short v[0:1], v2, off
	v_cndmask_b32_e64 v0, -v58, v58, vcc
	v_mad_u32_u24 v176, v156, s89, v227
	v_cvt_pk_bf16_f32 v2, v0, s0
	v_lshl_add_u64 v[0:1], v[10:11], 0, v[176:177]
	global_store_short v[0:1], v2, off
	v_cndmask_b32_e64 v0, -v57, v57, vcc
	v_mul_u32_u24_e32 v176, 0x300, v234
	v_cvt_pk_bf16_f32 v2, v0, s0
	v_lshl_add_u64 v[0:1], v[8:9], 0, v[176:177]
	global_store_short v[0:1], v2, off
	v_cndmask_b32_e64 v0, -v56, v56, vcc
	v_mad_u32_u24 v176, v156, s89, v228
	v_cvt_pk_bf16_f32 v2, v0, s0
	v_lshl_add_u64 v[0:1], v[10:11], 0, v[176:177]
	ds_bpermute_b32 v25, v237, v43
	global_store_short v[0:1], v2, off
	v_cndmask_b32_e64 v0, -v43, v43, vcc
	v_mul_u32_u24_e32 v176, 0x300, v235
	v_cvt_pk_bf16_f32 v2, v0, s0
	v_lshl_add_u64 v[0:1], v[8:9], 0, v[176:177]
	global_store_short v[0:1], v2, off
	v_and_b32_e32 v1, 0xffff0000, v41
	v_fmac_f32_e32 v27, v14, v1
	v_lshlrev_b32_e32 v1, 16, v42
	v_fmac_f32_e32 v27, v15, v1
	v_and_b32_e32 v1, 0xffff0000, v42
	v_cndmask_b32_e64 v0, -v47, v47, vcc
	v_fmac_f32_e32 v27, v24, v1
	s_waitcnt lgkmcnt(0)
	v_cndmask_b32_e64 v1, v43, v25, s[0:1]
	v_lshlrev_b32_e32 v2, 16, v28
	v_mad_u32_u24 v176, v156, s89, v229
	v_fmac_f32_e32 v27, v1, v2
	v_cvt_pk_bf16_f32 v2, v0, s0
	v_lshl_add_u64 v[0:1], v[10:11], 0, v[176:177]
	global_store_short v[0:1], v2, off
	v_cndmask_b32_e64 v0, -v27, v27, vcc
	v_mul_i32_i24_e32 v176, 0x300, v155
	v_cvt_pk_bf16_f32 v2, v0, s0
	v_lshl_add_u64 v[0:1], v[8:9], 0, v[176:177]
	global_store_short v[0:1], v2, off
	s_waitcnt vmcnt(63) expcnt(7) lgkmcnt(15)
	s_barrier
